# v079 + GEMM loops: s_setprio 1 issued before the opening barrier so the MFMA block starts with its first MFMA right after the barrier
# speedup vs baseline: 1.0073x; 1.0042x over previous
;     __device__ bool next(int i, Unit& u) const { if (!b.next(i / 3, u)) return false; u.pz = i % 3; return true; }
; #define PG8_STAGE(bufoff, gbase, voff) do { _Pragma("unroll") for (int _i = 0; _i < 2; ++_i) \
;         __builtin_amdgcn_global_load_lds((const gunsigned*)((const gchar*)(gbase) + (voff)[_i]), (LAS unsigned*)(lds + (bufoff) + ldsw + _i * 8192), 16, 0, 0); } while (0)
; #define PG8_LDA(dst, b, h) do { _Pragma("unroll") for (int m = 0; m < 4; ++m) _Pragma("unroll") for (int k = 0; k < 2; ++k) dst[m][k] = *(const LAS bf16x8*)(lds + PG8_SA(b, h) + aoff + m * 2048 + k * 1024); } while (0)
; #define PG8_LDB(dst, b, h) do { _Pragma("unroll") for (int n = 0; n < 2; ++n) _Pragma("unroll") for (int k = 0; k < 2; ++k) dst[n][k] = *(const LAS bf16x8*)(lds + PG8_SB(b, h) + boff + n * 2048 + k * 1024); } while (0)
; #define PG8_WAIT_V(n) asm volatile("s_waitcnt vmcnt(" #n ")" ::: "memory")
; #define PG8_WAIT_L(n) asm volatile("s_waitcnt lgkmcnt(" #n ")" ::: "memory")
; #define PG8_BAR __builtin_amdgcn_s_barrier()
; template <class Epi, class Sched>
; __device__ __forceinline__ void gemm_phase(LAS unsigned char* lds, const int tid, const Gemm g, const Sched& S, const Epi& E) {
;     ...
;         const bool has_next = S.next(ui + 1, nxt);
;         const gchar* nA = has_next ? (const gchar*)g.A + (size_t)nxt.pm * tstep + (size_t)nxt.pz * g.zA : cA;
;         const gchar* nB = has_next ? (const gchar*)g.Bt + (size_t)nxt.pn * tstep + (size_t)nxt.pz * g.zB : cB;
;         for (int t = 0; t < nt; t += 2) {
;             const bool last = (t == nt - 2);
;             const gchar* a1 = cA + (size_t)(t + 1) * kstep;
;             const gchar* a2 = last ? nA : cA + (size_t)(t + 2) * kstep; const gchar* b2 = last ? nB : cB + (size_t)(t + 2) * kstep;
;             const gchar* a3 = a2 + kstep; const gchar* b3 = b2 + kstep;
;             PG8_LDB(B0, 0, 0); PG8_LDB(B1, 0, 1); PG8_SCHED; PG8_LDA(At, 0, 0); PG8_STAGE(PG8_SA(1, 1), a1 + hstep, voffA);
;             PG8_WAIT_V(8); PG8_WAIT_L(0); PG8_BAR; PG8_MMA(0, 0, At, B0); PG8_MMA(0, 1, At, B1); PG8_BAR; PG8_SCHED;
;             PG8_LDA(At, 0, 1); PG8_STAGE(PG8_SB(0, 0), b2, voffB); PG8_STAGE(PG8_SB(0, 1), b2 + hstep, voffB); PG8_STAGE(PG8_SA(0, 0), a2, voffA);
;             PG8_WAIT_V(8); PG8_WAIT_L(0); PG8_BAR; PG8_MMA(1, 0, At, B0); PG8_MMA(1, 1, At, B1); PG8_BAR; PG8_SCHED;
.LBB0_319:
	s_add_u32 vcc_lo, s10, 0x100
	s_addc_u32 vcc_hi, s11, 0
	s_add_i32 s39, 0, 0x10000
	s_cmp_eq_u32 s29, 40
	s_cselect_b32 s75, s21, vcc_hi
	s_cselect_b32 s74, s20, vcc_lo
	s_cselect_b32 s73, s1, s93
	s_cselect_b32 s72, s0, s31
	s_add_i32 s30, 0, 0x14000
	v_add_u32_e32 v142, s39, v174
	v_add_u32_e32 v168, s30, v174
	ds_read_b128 v[130:133], v142
	ds_read_b128 v[134:137], v142 offset:1024
	ds_read_b128 v[138:141], v142 offset:2048
	ds_read_b128 v[142:145], v142 offset:3072
	ds_read_b128 v[146:149], v168
	ds_read_b128 v[150:153], v168 offset:1024
	ds_read_b128 v[164:167], v168 offset:2048
	ds_read_b128 v[168:171], v168 offset:3072
	s_add_i32 m0, s46, 0xc000
	ds_read_b128 v[192:195], v190
	ds_read_b128 v[204:207], v190 offset:1024
	ds_read_b128 v[208:211], v190 offset:2048
	ds_read_b128 v[212:215], v190 offset:3072
	ds_read_b128 v[216:219], v190 offset:4096
	ds_read_b128 v[220:223], v190 offset:5120
	ds_read_b128 v[224:227], v190 offset:6144
	ds_read_b128 v[242:245], v190 offset:7168
	global_load_lds_dwordx4 v162, s[10:11]
	s_add_i32 m0, s46, 0xe000
	s_nop 0
	global_load_lds_dwordx4 v160, s[10:11]
	s_waitcnt vmcnt(8)
	s_waitcnt lgkmcnt(0)
	s_setprio 1
	s_barrier
	v_mfma_f32_16x16x32_bf16 v[126:129], v[130:133], v[192:195], v[126:129]
	v_mfma_f32_16x16x32_bf16 v[122:125], v[138:141], v[192:195], v[122:125]
	v_mfma_f32_16x16x32_bf16 v[110:113], v[130:133], v[208:211], v[110:113]
	v_mfma_f32_16x16x32_bf16 v[106:109], v[138:141], v[208:211], v[106:109]
	v_mfma_f32_16x16x32_bf16 v[94:97], v[130:133], v[216:219], v[94:97]
	v_mfma_f32_16x16x32_bf16 v[90:93], v[138:141], v[216:219], v[90:93]
	v_mfma_f32_16x16x32_bf16 v[78:81], v[130:133], v[224:227], v[78:81]
	v_mfma_f32_16x16x32_bf16 v[74:77], v[138:141], v[224:227], v[74:77]
	v_mfma_f32_16x16x32_bf16 v[126:129], v[134:137], v[204:207], v[126:129]
	v_mfma_f32_16x16x32_bf16 v[122:125], v[142:145], v[204:207], v[122:125]
	v_mfma_f32_16x16x32_bf16 v[110:113], v[134:137], v[212:215], v[110:113]
	v_mfma_f32_16x16x32_bf16 v[106:109], v[142:145], v[212:215], v[106:109]
	v_mfma_f32_16x16x32_bf16 v[94:97], v[134:137], v[220:223], v[94:97]
	v_mfma_f32_16x16x32_bf16 v[90:93], v[142:145], v[220:223], v[90:93]
	v_mfma_f32_16x16x32_bf16 v[78:81], v[134:137], v[242:245], v[78:81]
	v_mfma_f32_16x16x32_bf16 v[74:77], v[142:145], v[242:245], v[74:77]
	s_setprio 0
	s_setprio 1
	v_mfma_f32_16x16x32_bf16 v[118:121], v[146:149], v[192:195], v[118:121]
	v_mfma_f32_16x16x32_bf16 v[114:117], v[164:167], v[192:195], v[114:117]
	v_mfma_f32_16x16x32_bf16 v[102:105], v[146:149], v[208:211], v[102:105]
	v_mfma_f32_16x16x32_bf16 v[98:101], v[164:167], v[208:211], v[98:101]
	v_mfma_f32_16x16x32_bf16 v[86:89], v[146:149], v[216:219], v[86:89]
	v_mfma_f32_16x16x32_bf16 v[82:85], v[164:167], v[216:219], v[82:85]
	v_mfma_f32_16x16x32_bf16 v[70:73], v[146:149], v[224:227], v[70:73]
	v_mfma_f32_16x16x32_bf16 v[66:69], v[164:167], v[224:227], v[66:69]
	v_mfma_f32_16x16x32_bf16 v[118:121], v[150:153], v[204:207], v[118:121]
	v_mfma_f32_16x16x32_bf16 v[114:117], v[168:171], v[204:207], v[114:117]
	v_mfma_f32_16x16x32_bf16 v[102:105], v[150:153], v[212:215], v[102:105]
	v_mfma_f32_16x16x32_bf16 v[98:101], v[168:171], v[212:215], v[98:101]
	v_mfma_f32_16x16x32_bf16 v[86:89], v[150:153], v[220:223], v[86:89]
	v_mfma_f32_16x16x32_bf16 v[82:85], v[168:171], v[220:223], v[82:85]
	v_mfma_f32_16x16x32_bf16 v[70:73], v[150:153], v[242:245], v[70:73]
	v_mfma_f32_16x16x32_bf16 v[66:69], v[168:171], v[242:245], v[66:69]
	s_barrier
	s_setprio 0
	s_add_i32 s10, s39, s43
	s_mov_b32 m0, s10
	ds_read_b128 v[192:195], v190 offset:16384
	ds_read_b128 v[204:207], v190 offset:17408
	ds_read_b128 v[208:211], v190 offset:18432
	ds_read_b128 v[212:215], v190 offset:19456
	ds_read_b128 v[216:219], v190 offset:20480
	ds_read_b128 v[220:223], v190 offset:21504
	ds_read_b128 v[224:227], v190 offset:22528
	ds_read_b128 v[242:245], v190 offset:23552
	global_load_lds_dwordx4 v0, s[72:73]
	s_add_i32 m0, s10, 0x2000
	s_add_u32 s10, s72, 0xb0000
	s_addc_u32 s11, s73, 0
	s_add_i32 s30, s30, s43
	global_load_lds_dwordx4 v158, s[72:73]
	s_mov_b32 m0, s30
	s_nop 0
	global_load_lds_dwordx4 v0, s[10:11]
	s_add_i32 m0, s30, 0x2000
	s_nop 0
	global_load_lds_dwordx4 v158, s[10:11]
	s_mov_b32 m0, s46
	s_nop 0
	global_load_lds_dwordx4 v154, s[74:75]
	s_mov_b32 m0, s47
	s_nop 0
	global_load_lds_dwordx4 v156, s[74:75]
	s_waitcnt vmcnt(8)
	s_waitcnt lgkmcnt(0)
	s_setprio 1
	s_barrier
	v_mfma_f32_16x16x32_bf16 v[62:65], v[130:133], v[192:195], v[62:65]
	v_mfma_f32_16x16x32_bf16 v[58:61], v[138:141], v[192:195], v[58:61]
	v_mfma_f32_16x16x32_bf16 v[46:49], v[130:133], v[208:211], v[46:49]
	v_mfma_f32_16x16x32_bf16 v[42:45], v[138:141], v[208:211], v[42:45]
	v_mfma_f32_16x16x32_bf16 v[30:33], v[130:133], v[216:219], v[30:33]
	v_mfma_f32_16x16x32_bf16 v[26:29], v[138:141], v[216:219], v[26:29]
	v_mfma_f32_16x16x32_bf16 v[14:17], v[130:133], v[224:227], v[14:17]
	v_mfma_f32_16x16x32_bf16 v[10:13], v[138:141], v[224:227], v[10:13]
	v_mfma_f32_16x16x32_bf16 v[62:65], v[134:137], v[204:207], v[62:65]
	v_mfma_f32_16x16x32_bf16 v[58:61], v[142:145], v[204:207], v[58:61]
	v_mfma_f32_16x16x32_bf16 v[46:49], v[134:137], v[212:215], v[46:49]
	v_mfma_f32_16x16x32_bf16 v[42:45], v[142:145], v[212:215], v[42:45]
	v_mfma_f32_16x16x32_bf16 v[30:33], v[134:137], v[220:223], v[30:33]
	v_mfma_f32_16x16x32_bf16 v[26:29], v[142:145], v[220:223], v[26:29]
	v_mfma_f32_16x16x32_bf16 v[14:17], v[134:137], v[242:245], v[14:17]
	v_mfma_f32_16x16x32_bf16 v[10:13], v[142:145], v[242:245], v[10:13]
	s_setprio 0
	s_setprio 1
	v_mfma_f32_16x16x32_bf16 v[54:57], v[146:149], v[192:195], v[54:57]
	v_mfma_f32_16x16x32_bf16 v[50:53], v[164:167], v[192:195], v[50:53]
	v_mfma_f32_16x16x32_bf16 v[38:41], v[146:149], v[208:211], v[38:41]
	v_mfma_f32_16x16x32_bf16 v[34:37], v[164:167], v[208:211], v[34:37]
	v_mfma_f32_16x16x32_bf16 v[22:25], v[146:149], v[216:219], v[22:25]
	v_mfma_f32_16x16x32_bf16 v[18:21], v[164:167], v[216:219], v[18:21]
	v_mfma_f32_16x16x32_bf16 v[6:9], v[146:149], v[224:227], v[6:9]
	v_mfma_f32_16x16x32_bf16 v[2:5], v[164:167], v[224:227], v[2:5]
	v_mfma_f32_16x16x32_bf16 v[54:57], v[150:153], v[204:207], v[54:57]
	v_mfma_f32_16x16x32_bf16 v[50:53], v[168:171], v[204:207], v[50:53]
	v_mfma_f32_16x16x32_bf16 v[38:41], v[150:153], v[212:215], v[38:41]
	v_mfma_f32_16x16x32_bf16 v[34:37], v[168:171], v[212:215], v[34:37]
	v_mfma_f32_16x16x32_bf16 v[22:25], v[150:153], v[220:223], v[22:25]
	v_mfma_f32_16x16x32_bf16 v[18:21], v[168:171], v[220:223], v[18:21]
	v_mfma_f32_16x16x32_bf16 v[6:9], v[150:153], v[242:245], v[6:9]
	v_mfma_f32_16x16x32_bf16 v[2:5], v[168:171], v[242:245], v[2:5]
	s_barrier
; #define PG8_STAGE(bufoff, gbase, voff) do { _Pragma("unroll") for (int _i = 0; _i < 2; ++_i) \
;         __builtin_amdgcn_global_load_lds((const gunsigned*)((const gchar*)(gbase) + (voff)[_i]), (LAS unsigned*)(lds + (bufoff) + ldsw + _i * 8192), 16, 0, 0); } while (0)
; #define PG8_LDA(dst, b, h) do { _Pragma("unroll") for (int m = 0; m < 4; ++m) _Pragma("unroll") for (int k = 0; k < 2; ++k) dst[m][k] = *(const LAS bf16x8*)(lds + PG8_SA(b, h) + aoff + m * 2048 + k * 1024); } while (0)
; #define PG8_LDB(dst, b, h) do { _Pragma("unroll") for (int n = 0; n < 2; ++n) _Pragma("unroll") for (int k = 0; k < 2; ++k) dst[n][k] = *(const LAS bf16x8*)(lds + PG8_SB(b, h) + boff + n * 2048 + k * 1024); } while (0)
; #define PG8_MMA(ai, bj, At, Bt) do { __builtin_amdgcn_s_setprio(1); _Pragma("unroll") for (int m = 0; m < 4; ++m) _Pragma("unroll") for (int n = 0; n < 2; ++n) _Pragma("unroll") for (int k = 0; k < 2; ++k) \
;         acc[ai][bj][m][n] = __builtin_amdgcn_mfma_f32_16x16x32_bf16(Bt[n][k], At[m][k], acc[ai][bj][m][n], 0, 0, 0); __builtin_amdgcn_s_setprio(0); } while (0)
; #define PG8_WAIT_V(n) asm volatile("s_waitcnt vmcnt(" #n ")" ::: "memory")
; #define PG8_WAIT_L(n) asm volatile("s_waitcnt lgkmcnt(" #n ")" ::: "memory")
; #define PG8_BAR __builtin_amdgcn_s_barrier()
; #define PG8_SCHED __builtin_amdgcn_sched_barrier(0)
; template <class Epi, class Sched>
; __device__ __forceinline__ void gemm_phase(LAS unsigned char* lds, const int tid, const Gemm g, const Sched& S, const Epi& E) {
;     ...
;             PG8_LDB(B0, 1, 0); PG8_LDB(B1, 1, 1); PG8_SCHED; PG8_LDA(At, 1, 0); PG8_STAGE(PG8_SA(0, 1), a2 + hstep, voffA);
;             PG8_WAIT_V(8); PG8_WAIT_L(0); PG8_BAR; PG8_MMA(0, 0, At, B0); PG8_MMA(0, 1, At, B1); PG8_BAR; PG8_SCHED;
;             PG8_LDA(At, 1, 1); PG8_STAGE(PG8_SB(1, 0), b3, voffB); PG8_STAGE(PG8_SB(1, 1), b3 + hstep, voffB); PG8_STAGE(PG8_SA(1, 0), a3, voffA);
;             PG8_WAIT_V(8); PG8_WAIT_L(0); PG8_BAR; PG8_MMA(1, 0, At, B0); PG8_MMA(1, 1, At, B1); PG8_BAR; PG8_SCHED;
;         }
	s_setprio 0
	s_add_i32 s30, 0, 0x18000
	s_add_i32 s39, 0, 0x1c000
	v_add_u32_e32 v142, s30, v174
	v_add_u32_e32 v168, s39, v174
	ds_read_b128 v[130:133], v142
	ds_read_b128 v[134:137], v142 offset:1024
	ds_read_b128 v[138:141], v142 offset:2048
	ds_read_b128 v[142:145], v142 offset:3072
	ds_read_b128 v[146:149], v168
	ds_read_b128 v[150:153], v168 offset:1024
	ds_read_b128 v[164:167], v168 offset:2048
	ds_read_b128 v[168:171], v168 offset:3072
	s_add_u32 s10, s74, 0xb0000
	s_addc_u32 s11, s75, 0
	s_mov_b32 m0, s48
	ds_read_b128 v[192:195], v190 offset:32768
	ds_read_b128 v[204:207], v190 offset:33792
	ds_read_b128 v[208:211], v190 offset:34816
	ds_read_b128 v[212:215], v190 offset:35840
	ds_read_b128 v[216:219], v190 offset:36864
	ds_read_b128 v[220:223], v190 offset:37888
	ds_read_b128 v[224:227], v190 offset:38912
	ds_read_b128 v[242:245], v190 offset:39936
	global_load_lds_dwordx4 v154, s[10:11]
	s_mov_b32 m0, s49
	s_nop 0
	global_load_lds_dwordx4 v156, s[10:11]
	s_waitcnt vmcnt(8)
	s_waitcnt lgkmcnt(0)
	s_setprio 1
	s_barrier
	v_mfma_f32_16x16x32_bf16 v[126:129], v[130:133], v[192:195], v[126:129]
	v_mfma_f32_16x16x32_bf16 v[122:125], v[138:141], v[192:195], v[122:125]
	v_mfma_f32_16x16x32_bf16 v[110:113], v[130:133], v[208:211], v[110:113]
	v_mfma_f32_16x16x32_bf16 v[106:109], v[138:141], v[208:211], v[106:109]
	v_mfma_f32_16x16x32_bf16 v[94:97], v[130:133], v[216:219], v[94:97]
	v_mfma_f32_16x16x32_bf16 v[90:93], v[138:141], v[216:219], v[90:93]
	v_mfma_f32_16x16x32_bf16 v[78:81], v[130:133], v[224:227], v[78:81]
	v_mfma_f32_16x16x32_bf16 v[74:77], v[138:141], v[224:227], v[74:77]
	v_mfma_f32_16x16x32_bf16 v[126:129], v[134:137], v[204:207], v[126:129]
	v_mfma_f32_16x16x32_bf16 v[122:125], v[142:145], v[204:207], v[122:125]
	v_mfma_f32_16x16x32_bf16 v[110:113], v[134:137], v[212:215], v[110:113]
	v_mfma_f32_16x16x32_bf16 v[106:109], v[142:145], v[212:215], v[106:109]
	v_mfma_f32_16x16x32_bf16 v[94:97], v[134:137], v[220:223], v[94:97]
	v_mfma_f32_16x16x32_bf16 v[90:93], v[142:145], v[220:223], v[90:93]
	v_mfma_f32_16x16x32_bf16 v[78:81], v[134:137], v[242:245], v[78:81]
	v_mfma_f32_16x16x32_bf16 v[74:77], v[142:145], v[242:245], v[74:77]
	s_setprio 0
	s_setprio 1
	v_mfma_f32_16x16x32_bf16 v[118:121], v[146:149], v[192:195], v[118:121]
	v_mfma_f32_16x16x32_bf16 v[114:117], v[164:167], v[192:195], v[114:117]
	v_mfma_f32_16x16x32_bf16 v[102:105], v[146:149], v[208:211], v[102:105]
	v_mfma_f32_16x16x32_bf16 v[98:101], v[164:167], v[208:211], v[98:101]
	v_mfma_f32_16x16x32_bf16 v[86:89], v[146:149], v[216:219], v[86:89]
	v_mfma_f32_16x16x32_bf16 v[82:85], v[164:167], v[216:219], v[82:85]
	v_mfma_f32_16x16x32_bf16 v[70:73], v[146:149], v[224:227], v[70:73]
	v_mfma_f32_16x16x32_bf16 v[66:69], v[164:167], v[224:227], v[66:69]
	v_mfma_f32_16x16x32_bf16 v[118:121], v[150:153], v[204:207], v[118:121]
	v_mfma_f32_16x16x32_bf16 v[114:117], v[168:171], v[204:207], v[114:117]
	v_mfma_f32_16x16x32_bf16 v[102:105], v[150:153], v[212:215], v[102:105]
	v_mfma_f32_16x16x32_bf16 v[98:101], v[168:171], v[212:215], v[98:101]
	v_mfma_f32_16x16x32_bf16 v[86:89], v[150:153], v[220:223], v[86:89]
	v_mfma_f32_16x16x32_bf16 v[82:85], v[168:171], v[220:223], v[82:85]
	v_mfma_f32_16x16x32_bf16 v[70:73], v[150:153], v[242:245], v[70:73]
	v_mfma_f32_16x16x32_bf16 v[66:69], v[168:171], v[242:245], v[66:69]
	s_barrier
	s_setprio 0
	s_add_i32 s10, s30, s43
	s_mov_b32 m0, s10
	ds_read_b128 v[192:195], v190 offset:49152
	ds_read_b128 v[204:207], v190 offset:50176
	ds_read_b128 v[208:211], v190 offset:51200
	ds_read_b128 v[212:215], v190 offset:52224
	ds_read_b128 v[216:219], v190 offset:53248
	ds_read_b128 v[220:223], v190 offset:54272
	ds_read_b128 v[224:227], v190 offset:55296
	ds_read_b128 v[242:245], v190 offset:56320
	global_load_lds_dwordx4 v201, s[72:73]
	s_add_i32 m0, s10, 0x2000
	s_add_u32 s10, s72, 0xb0080
	s_addc_u32 s11, s73, 0
	s_add_i32 s30, s39, s43
	global_load_lds_dwordx4 v247, s[72:73]
	s_mov_b32 m0, s30
	s_nop 0
	global_load_lds_dwordx4 v0, s[10:11]
	s_add_i32 m0, s30, 0x2000
	s_nop 0
	global_load_lds_dwordx4 v158, s[10:11]
	s_mov_b32 m0, s53
	s_nop 0
	global_load_lds_dwordx4 v249, s[74:75]
	s_mov_b32 m0, s54
	s_nop 0
	global_load_lds_dwordx4 v251, s[74:75]
	s_waitcnt vmcnt(8)
	s_waitcnt lgkmcnt(0)
	s_setprio 1
	s_barrier
	v_mfma_f32_16x16x32_bf16 v[62:65], v[130:133], v[192:195], v[62:65]
	v_mfma_f32_16x16x32_bf16 v[58:61], v[138:141], v[192:195], v[58:61]
	v_mfma_f32_16x16x32_bf16 v[46:49], v[130:133], v[208:211], v[46:49]
	v_mfma_f32_16x16x32_bf16 v[42:45], v[138:141], v[208:211], v[42:45]
	v_mfma_f32_16x16x32_bf16 v[30:33], v[130:133], v[216:219], v[30:33]
	v_mfma_f32_16x16x32_bf16 v[26:29], v[138:141], v[216:219], v[26:29]
	v_mfma_f32_16x16x32_bf16 v[14:17], v[130:133], v[224:227], v[14:17]
	v_mfma_f32_16x16x32_bf16 v[10:13], v[138:141], v[224:227], v[10:13]
	v_mfma_f32_16x16x32_bf16 v[62:65], v[134:137], v[204:207], v[62:65]
	v_mfma_f32_16x16x32_bf16 v[58:61], v[142:145], v[204:207], v[58:61]
	v_mfma_f32_16x16x32_bf16 v[46:49], v[134:137], v[212:215], v[46:49]
	v_mfma_f32_16x16x32_bf16 v[42:45], v[142:145], v[212:215], v[42:45]
	v_mfma_f32_16x16x32_bf16 v[30:33], v[134:137], v[220:223], v[30:33]
	v_mfma_f32_16x16x32_bf16 v[26:29], v[142:145], v[220:223], v[26:29]
	v_mfma_f32_16x16x32_bf16 v[14:17], v[134:137], v[242:245], v[14:17]
	v_mfma_f32_16x16x32_bf16 v[10:13], v[142:145], v[242:245], v[10:13]
	s_setprio 0
	s_setprio 1
	v_mfma_f32_16x16x32_bf16 v[54:57], v[146:149], v[192:195], v[54:57]
	v_mfma_f32_16x16x32_bf16 v[50:53], v[164:167], v[192:195], v[50:53]
	v_mfma_f32_16x16x32_bf16 v[38:41], v[146:149], v[208:211], v[38:41]
	v_mfma_f32_16x16x32_bf16 v[34:37], v[164:167], v[208:211], v[34:37]
	v_mfma_f32_16x16x32_bf16 v[22:25], v[146:149], v[216:219], v[22:25]
	v_mfma_f32_16x16x32_bf16 v[18:21], v[164:167], v[216:219], v[18:21]
	v_mfma_f32_16x16x32_bf16 v[6:9], v[146:149], v[224:227], v[6:9]
	v_mfma_f32_16x16x32_bf16 v[2:5], v[164:167], v[224:227], v[2:5]
	v_mfma_f32_16x16x32_bf16 v[54:57], v[150:153], v[204:207], v[54:57]
	v_mfma_f32_16x16x32_bf16 v[50:53], v[168:171], v[204:207], v[50:53]
	v_mfma_f32_16x16x32_bf16 v[38:41], v[150:153], v[212:215], v[38:41]
	v_mfma_f32_16x16x32_bf16 v[34:37], v[168:171], v[212:215], v[34:37]
	v_mfma_f32_16x16x32_bf16 v[22:25], v[150:153], v[220:223], v[22:25]
	v_mfma_f32_16x16x32_bf16 v[18:21], v[168:171], v[220:223], v[18:21]
	v_mfma_f32_16x16x32_bf16 v[6:9], v[150:153], v[242:245], v[6:9]
	v_mfma_f32_16x16x32_bf16 v[2:5], v[168:171], v[242:245], v[2:5]
	s_barrier
	s_setprio 0
	s_add_i32 s29, s29, 2
	s_add_u32 s31, s31, 0x100
	s_addc_u32 s93, s93, 0
	s_cmp_gt_u32 s29, 41
	s_mov_b64 s[10:11], vcc
	s_cbranch_scc0 .LBB0_319
	s_and_b64 vcc, exec, s[16:17]
	s_cbranch_vccz .LBB0_322
	s_barrier

; #define PG8_STAGE(bufoff, gbase, voff) do { _Pragma("unroll") for (int _i = 0; _i < 2; ++_i) \
;         __builtin_amdgcn_global_load_lds((const gunsigned*)((const gchar*)(gbase) + (voff)[_i]), (LAS unsigned*)(lds + (bufoff) + ldsw + _i * 8192), 16, 0, 0); } while (0)
; #define PG8_LDA(dst, b, h) do { _Pragma("unroll") for (int m = 0; m < 4; ++m) _Pragma("unroll") for (int k = 0; k < 2; ++k) dst[m][k] = *(const LAS bf16x8*)(lds + PG8_SA(b, h) + aoff + m * 2048 + k * 1024); } while (0)
; #define PG8_LDB(dst, b, h) do { _Pragma("unroll") for (int n = 0; n < 2; ++n) _Pragma("unroll") for (int k = 0; k < 2; ++k) dst[n][k] = *(const LAS bf16x8*)(lds + PG8_SB(b, h) + boff + n * 2048 + k * 1024); } while (0)
; #define PG8_MMA(ai, bj, At, Bt) do { __builtin_amdgcn_s_setprio(1); _Pragma("unroll") for (int m = 0; m < 4; ++m) _Pragma("unroll") for (int n = 0; n < 2; ++n) _Pragma("unroll") for (int k = 0; k < 2; ++k) \
;         acc[ai][bj][m][n] = __builtin_amdgcn_mfma_f32_16x16x32_bf16(Bt[n][k], At[m][k], acc[ai][bj][m][n], 0, 0, 0); __builtin_amdgcn_s_setprio(0); } while (0)
; #define PG8_WAIT_V(n) asm volatile("s_waitcnt vmcnt(" #n ")" ::: "memory")
; #define PG8_WAIT_L(n) asm volatile("s_waitcnt lgkmcnt(" #n ")" ::: "memory")
; #define PG8_BAR __builtin_amdgcn_s_barrier()
; #define PG8_SCHED __builtin_amdgcn_sched_barrier(0)
; template <class Epi, class Sched>
; __device__ __forceinline__ void gemm_phase(LAS unsigned char* lds, const int tid, const Gemm g, const Sched& S, const Epi& E) {
;     ...
;         for (int t = 0; t < nt; t += 2) {
;             const bool last = (t == nt - 2);
;             const gchar* a1 = cA + (size_t)(t + 1) * kstep;
;             const gchar* a2 = last ? nA : cA + (size_t)(t + 2) * kstep; const gchar* b2 = last ? nB : cB + (size_t)(t + 2) * kstep;
;             const gchar* a3 = a2 + kstep; const gchar* b3 = b2 + kstep;
;             PG8_LDB(B0, 0, 0); PG8_LDB(B1, 0, 1); PG8_SCHED; PG8_LDA(At, 0, 0); PG8_STAGE(PG8_SA(1, 1), a1 + hstep, voffA);
;             PG8_WAIT_V(8); PG8_WAIT_L(0); PG8_BAR; PG8_MMA(0, 0, At, B0); PG8_MMA(0, 1, At, B1); PG8_BAR; PG8_SCHED;
;             PG8_LDA(At, 0, 1); PG8_STAGE(PG8_SB(0, 0), b2, voffB); PG8_STAGE(PG8_SB(0, 1), b2 + hstep, voffB); PG8_STAGE(PG8_SA(0, 0), a2, voffA);
;             PG8_WAIT_V(8); PG8_WAIT_L(0); PG8_BAR; PG8_MMA(1, 0, At, B0); PG8_MMA(1, 1, At, B1); PG8_BAR; PG8_SCHED;
.LBB0_369:
	s_add_u32 s20, s16, 0xfffc0080
	s_addc_u32 s21, s17, -1
	s_add_i32 s29, 0, 0x10000
	s_cmp_eq_u32 s31, 12
	s_cselect_b32 s57, s11, s21
	s_cselect_b32 s56, s12, s20
	v_add_u32_e32 v140, s29, v145
	s_cselect_b32 s21, s9, s24
	s_cselect_b32 s20, s15, s23
	s_add_i32 s30, 0, 0x14000
	ds_read_b128 v[146:149], v140
	ds_read_b128 v[156:159], v140 offset:1024
	ds_read_b128 v[160:163], v140 offset:2048
	ds_read_b128 v[164:167], v140 offset:3072
	v_add_u32_e32 v140, s30, v145
	ds_read_b128 v[168:171], v140
	ds_read_b128 v[172:175], v140 offset:1024
	ds_read_b128 v[176:179], v140 offset:2048
	ds_read_b128 v[180:183], v140 offset:3072
	s_add_i32 m0, s73, 0xc000
	ds_read_b128 v[184:187], v155
	ds_read_b128 v[188:191], v155 offset:1024
	ds_read_b128 v[192:195], v155 offset:2048
	ds_read_b128 v[204:207], v155 offset:3072
	ds_read_b128 v[208:211], v155 offset:4096
	ds_read_b128 v[212:215], v155 offset:5120
	ds_read_b128 v[216:219], v155 offset:6144
	ds_read_b128 v[220:223], v155 offset:7168
	global_load_lds_dwordx4 v138, s[16:17]
	s_add_i32 m0, s73, 0xe000
	s_nop 0
	global_load_lds_dwordx4 v136, s[16:17]
	s_waitcnt vmcnt(8)
	s_waitcnt lgkmcnt(0)
	s_setprio 1
	s_barrier
	v_mfma_f32_16x16x32_bf16 v[126:129], v[146:149], v[184:187], v[126:129]
	v_mfma_f32_16x16x32_bf16 v[118:121], v[160:163], v[184:187], v[118:121]
	v_mfma_f32_16x16x32_bf16 v[110:113], v[146:149], v[192:195], v[110:113]
	v_mfma_f32_16x16x32_bf16 v[102:105], v[160:163], v[192:195], v[102:105]
	v_mfma_f32_16x16x32_bf16 v[94:97], v[146:149], v[208:211], v[94:97]
	v_mfma_f32_16x16x32_bf16 v[86:89], v[160:163], v[208:211], v[86:89]
	v_mfma_f32_16x16x32_bf16 v[78:81], v[146:149], v[216:219], v[78:81]
	v_mfma_f32_16x16x32_bf16 v[70:73], v[160:163], v[216:219], v[70:73]
	v_mfma_f32_16x16x32_bf16 v[126:129], v[156:159], v[188:191], v[126:129]
	v_mfma_f32_16x16x32_bf16 v[118:121], v[164:167], v[188:191], v[118:121]
	v_mfma_f32_16x16x32_bf16 v[110:113], v[156:159], v[204:207], v[110:113]
	v_mfma_f32_16x16x32_bf16 v[102:105], v[164:167], v[204:207], v[102:105]
	v_mfma_f32_16x16x32_bf16 v[94:97], v[156:159], v[212:215], v[94:97]
	v_mfma_f32_16x16x32_bf16 v[86:89], v[164:167], v[212:215], v[86:89]
	v_mfma_f32_16x16x32_bf16 v[78:81], v[156:159], v[220:223], v[78:81]
	v_mfma_f32_16x16x32_bf16 v[70:73], v[164:167], v[220:223], v[70:73]
	s_setprio 0
	s_setprio 1
	v_mfma_f32_16x16x32_bf16 v[122:125], v[168:171], v[184:187], v[122:125]
	v_mfma_f32_16x16x32_bf16 v[114:117], v[176:179], v[184:187], v[114:117]
	v_mfma_f32_16x16x32_bf16 v[106:109], v[168:171], v[192:195], v[106:109]
	v_mfma_f32_16x16x32_bf16 v[98:101], v[176:179], v[192:195], v[98:101]
	v_mfma_f32_16x16x32_bf16 v[90:93], v[168:171], v[208:211], v[90:93]
	v_mfma_f32_16x16x32_bf16 v[82:85], v[176:179], v[208:211], v[82:85]
	v_mfma_f32_16x16x32_bf16 v[74:77], v[168:171], v[216:219], v[74:77]
	v_mfma_f32_16x16x32_bf16 v[66:69], v[176:179], v[216:219], v[66:69]
	v_mfma_f32_16x16x32_bf16 v[122:125], v[172:175], v[188:191], v[122:125]
	v_mfma_f32_16x16x32_bf16 v[114:117], v[180:183], v[188:191], v[114:117]
	v_mfma_f32_16x16x32_bf16 v[106:109], v[172:175], v[204:207], v[106:109]
	v_mfma_f32_16x16x32_bf16 v[98:101], v[180:183], v[204:207], v[98:101]
	v_mfma_f32_16x16x32_bf16 v[90:93], v[172:175], v[212:215], v[90:93]
	v_mfma_f32_16x16x32_bf16 v[82:85], v[180:183], v[212:215], v[82:85]
	v_mfma_f32_16x16x32_bf16 v[74:77], v[172:175], v[220:223], v[74:77]
	v_mfma_f32_16x16x32_bf16 v[66:69], v[180:183], v[220:223], v[66:69]
	s_barrier
	s_setprio 0
	s_add_i32 s29, s29, s43
	s_mov_b32 m0, s29
	ds_read_b128 v[184:187], v155 offset:16384
	ds_read_b128 v[188:191], v155 offset:17408
	ds_read_b128 v[192:195], v155 offset:18432
	ds_read_b128 v[204:207], v155 offset:19456
	ds_read_b128 v[208:211], v155 offset:20480
	ds_read_b128 v[212:215], v155 offset:21504
	ds_read_b128 v[216:219], v155 offset:22528
	ds_read_b128 v[220:223], v155 offset:23552
	global_load_lds_dwordx4 v0, s[20:21]
	s_add_i32 m0, s29, 0x2000
	s_add_u32 s46, s20, 0x40000
	s_addc_u32 s47, s21, 0
	s_add_i32 s29, s30, s43
	global_load_lds_dwordx4 v130, s[20:21]
	s_mov_b32 m0, s29
	s_nop 0
	global_load_lds_dwordx4 v0, s[46:47]
	s_add_i32 m0, s29, 0x2000
	s_nop 0
	global_load_lds_dwordx4 v130, s[46:47]
	s_mov_b32 m0, s73
	s_nop 0
	global_load_lds_dwordx4 v134, s[56:57]
	s_mov_b32 m0, s74
	s_nop 0
	global_load_lds_dwordx4 v132, s[56:57]
	s_waitcnt vmcnt(8)
	s_waitcnt lgkmcnt(0)
	s_setprio 1
	s_barrier
	v_mfma_f32_16x16x32_bf16 v[62:65], v[146:149], v[184:187], v[62:65]
	v_mfma_f32_16x16x32_bf16 v[54:57], v[160:163], v[184:187], v[54:57]
	v_mfma_f32_16x16x32_bf16 v[46:49], v[146:149], v[192:195], v[46:49]
	v_mfma_f32_16x16x32_bf16 v[38:41], v[160:163], v[192:195], v[38:41]
	v_mfma_f32_16x16x32_bf16 v[30:33], v[146:149], v[208:211], v[30:33]
	v_mfma_f32_16x16x32_bf16 v[22:25], v[160:163], v[208:211], v[22:25]
	v_mfma_f32_16x16x32_bf16 v[14:17], v[146:149], v[216:219], v[14:17]
	v_mfma_f32_16x16x32_bf16 v[6:9], v[160:163], v[216:219], v[6:9]
	v_mfma_f32_16x16x32_bf16 v[62:65], v[156:159], v[188:191], v[62:65]
	v_mfma_f32_16x16x32_bf16 v[54:57], v[164:167], v[188:191], v[54:57]
	v_mfma_f32_16x16x32_bf16 v[46:49], v[156:159], v[204:207], v[46:49]
	v_mfma_f32_16x16x32_bf16 v[38:41], v[164:167], v[204:207], v[38:41]
	v_mfma_f32_16x16x32_bf16 v[30:33], v[156:159], v[212:215], v[30:33]
	v_mfma_f32_16x16x32_bf16 v[22:25], v[164:167], v[212:215], v[22:25]
	v_mfma_f32_16x16x32_bf16 v[14:17], v[156:159], v[220:223], v[14:17]
	v_mfma_f32_16x16x32_bf16 v[6:9], v[164:167], v[220:223], v[6:9]
	s_setprio 0
	s_setprio 1
	v_mfma_f32_16x16x32_bf16 v[58:61], v[168:171], v[184:187], v[58:61]
	v_mfma_f32_16x16x32_bf16 v[50:53], v[176:179], v[184:187], v[50:53]
	v_mfma_f32_16x16x32_bf16 v[42:45], v[168:171], v[192:195], v[42:45]
	v_mfma_f32_16x16x32_bf16 v[34:37], v[176:179], v[192:195], v[34:37]
	v_mfma_f32_16x16x32_bf16 v[26:29], v[168:171], v[208:211], v[26:29]
	v_mfma_f32_16x16x32_bf16 v[18:21], v[176:179], v[208:211], v[18:21]
	v_mfma_f32_16x16x32_bf16 v[10:13], v[168:171], v[216:219], v[10:13]
	v_mfma_f32_16x16x32_bf16 v[2:5], v[176:179], v[216:219], v[2:5]
	v_mfma_f32_16x16x32_bf16 v[58:61], v[172:175], v[188:191], v[58:61]
	v_mfma_f32_16x16x32_bf16 v[50:53], v[180:183], v[188:191], v[50:53]
	v_mfma_f32_16x16x32_bf16 v[42:45], v[172:175], v[204:207], v[42:45]
	v_mfma_f32_16x16x32_bf16 v[34:37], v[180:183], v[204:207], v[34:37]
	v_mfma_f32_16x16x32_bf16 v[26:29], v[172:175], v[212:215], v[26:29]
	v_mfma_f32_16x16x32_bf16 v[18:21], v[180:183], v[212:215], v[18:21]
	v_mfma_f32_16x16x32_bf16 v[10:13], v[172:175], v[220:223], v[10:13]
	v_mfma_f32_16x16x32_bf16 v[2:5], v[180:183], v[220:223], v[2:5]
	s_barrier
; #define PG8_STAGE(bufoff, gbase, voff) do { _Pragma("unroll") for (int _i = 0; _i < 2; ++_i) \
;         __builtin_amdgcn_global_load_lds((const gunsigned*)((const gchar*)(gbase) + (voff)[_i]), (LAS unsigned*)(lds + (bufoff) + ldsw + _i * 8192), 16, 0, 0); } while (0)
; #define PG8_LDA(dst, b, h) do { _Pragma("unroll") for (int m = 0; m < 4; ++m) _Pragma("unroll") for (int k = 0; k < 2; ++k) dst[m][k] = *(const LAS bf16x8*)(lds + PG8_SA(b, h) + aoff + m * 2048 + k * 1024); } while (0)
; #define PG8_LDB(dst, b, h) do { _Pragma("unroll") for (int n = 0; n < 2; ++n) _Pragma("unroll") for (int k = 0; k < 2; ++k) dst[n][k] = *(const LAS bf16x8*)(lds + PG8_SB(b, h) + boff + n * 2048 + k * 1024); } while (0)
; #define PG8_MMA(ai, bj, At, Bt) do { __builtin_amdgcn_s_setprio(1); _Pragma("unroll") for (int m = 0; m < 4; ++m) _Pragma("unroll") for (int n = 0; n < 2; ++n) _Pragma("unroll") for (int k = 0; k < 2; ++k) \
;         acc[ai][bj][m][n] = __builtin_amdgcn_mfma_f32_16x16x32_bf16(Bt[n][k], At[m][k], acc[ai][bj][m][n], 0, 0, 0); __builtin_amdgcn_s_setprio(0); } while (0)
; #define PG8_WAIT_V(n) asm volatile("s_waitcnt vmcnt(" #n ")" ::: "memory")
; #define PG8_WAIT_L(n) asm volatile("s_waitcnt lgkmcnt(" #n ")" ::: "memory")
; #define PG8_BAR __builtin_amdgcn_s_barrier()
; #define PG8_SCHED __builtin_amdgcn_sched_barrier(0)
; template <class Epi, class Sched>
; __device__ __forceinline__ void gemm_phase(LAS unsigned char* lds, const int tid, const Gemm g, const Sched& S, const Epi& E) {
;     ...
;             PG8_LDB(B0, 1, 0); PG8_LDB(B1, 1, 1); PG8_SCHED; PG8_LDA(At, 1, 0); PG8_STAGE(PG8_SA(0, 1), a2 + hstep, voffA);
;             PG8_WAIT_V(8); PG8_WAIT_L(0); PG8_BAR; PG8_MMA(0, 0, At, B0); PG8_MMA(0, 1, At, B1); PG8_BAR; PG8_SCHED;
;             PG8_LDA(At, 1, 1); PG8_STAGE(PG8_SB(1, 0), b3, voffB); PG8_STAGE(PG8_SB(1, 1), b3 + hstep, voffB); PG8_STAGE(PG8_SA(1, 0), a3, voffA);
;             PG8_WAIT_V(8); PG8_WAIT_L(0); PG8_BAR; PG8_MMA(1, 0, At, B0); PG8_MMA(1, 1, At, B1); PG8_BAR; PG8_SCHED;
;         }
;         if (wr == 0) PG8_BAR;
	s_setprio 0
	s_add_i32 s29, 0, 0x18000
	v_add_u32_e32 v142, s29, v145
	s_add_i32 s30, 0, 0x1c000
	ds_read_b128 v[146:149], v142
	ds_read_b128 v[156:159], v142 offset:1024
	ds_read_b128 v[160:163], v142 offset:2048
	ds_read_b128 v[164:167], v142 offset:3072
	v_add_u32_e32 v142, s30, v145
	ds_read_b128 v[168:171], v142
	ds_read_b128 v[172:175], v142 offset:1024
	ds_read_b128 v[176:179], v142 offset:2048
	ds_read_b128 v[180:183], v142 offset:3072
	s_add_u32 s46, s56, 0x40000
	s_addc_u32 s47, s57, 0
	s_mov_b32 m0, s75
	ds_read_b128 v[184:187], v155 offset:32768
	ds_read_b128 v[188:191], v155 offset:33792
	ds_read_b128 v[192:195], v155 offset:34816
	ds_read_b128 v[204:207], v155 offset:35840
	ds_read_b128 v[208:211], v155 offset:36864
	ds_read_b128 v[212:215], v155 offset:37888
	ds_read_b128 v[216:219], v155 offset:38912
	ds_read_b128 v[220:223], v155 offset:39936
	global_load_lds_dwordx4 v134, s[46:47]
	s_mov_b32 m0, s92
	s_nop 0
	global_load_lds_dwordx4 v132, s[46:47]
	s_waitcnt vmcnt(8)
	s_waitcnt lgkmcnt(0)
	s_setprio 1
	s_barrier
	v_mfma_f32_16x16x32_bf16 v[126:129], v[146:149], v[184:187], v[126:129]
	v_mfma_f32_16x16x32_bf16 v[118:121], v[160:163], v[184:187], v[118:121]
	v_mfma_f32_16x16x32_bf16 v[110:113], v[146:149], v[192:195], v[110:113]
	v_mfma_f32_16x16x32_bf16 v[102:105], v[160:163], v[192:195], v[102:105]
	v_mfma_f32_16x16x32_bf16 v[94:97], v[146:149], v[208:211], v[94:97]
	v_mfma_f32_16x16x32_bf16 v[86:89], v[160:163], v[208:211], v[86:89]
	v_mfma_f32_16x16x32_bf16 v[78:81], v[146:149], v[216:219], v[78:81]
	v_mfma_f32_16x16x32_bf16 v[70:73], v[160:163], v[216:219], v[70:73]
	v_mfma_f32_16x16x32_bf16 v[126:129], v[156:159], v[188:191], v[126:129]
	v_mfma_f32_16x16x32_bf16 v[118:121], v[164:167], v[188:191], v[118:121]
	v_mfma_f32_16x16x32_bf16 v[110:113], v[156:159], v[204:207], v[110:113]
	v_mfma_f32_16x16x32_bf16 v[102:105], v[164:167], v[204:207], v[102:105]
	v_mfma_f32_16x16x32_bf16 v[94:97], v[156:159], v[212:215], v[94:97]
	v_mfma_f32_16x16x32_bf16 v[86:89], v[164:167], v[212:215], v[86:89]
	v_mfma_f32_16x16x32_bf16 v[78:81], v[156:159], v[220:223], v[78:81]
	v_mfma_f32_16x16x32_bf16 v[70:73], v[164:167], v[220:223], v[70:73]
	s_setprio 0
	s_setprio 1
	v_mfma_f32_16x16x32_bf16 v[122:125], v[168:171], v[184:187], v[122:125]
	v_mfma_f32_16x16x32_bf16 v[114:117], v[176:179], v[184:187], v[114:117]
	v_mfma_f32_16x16x32_bf16 v[106:109], v[168:171], v[192:195], v[106:109]
	v_mfma_f32_16x16x32_bf16 v[98:101], v[176:179], v[192:195], v[98:101]
	v_mfma_f32_16x16x32_bf16 v[90:93], v[168:171], v[208:211], v[90:93]
	v_mfma_f32_16x16x32_bf16 v[82:85], v[176:179], v[208:211], v[82:85]
	v_mfma_f32_16x16x32_bf16 v[74:77], v[168:171], v[216:219], v[74:77]
	v_mfma_f32_16x16x32_bf16 v[66:69], v[176:179], v[216:219], v[66:69]
	v_mfma_f32_16x16x32_bf16 v[122:125], v[172:175], v[188:191], v[122:125]
	v_mfma_f32_16x16x32_bf16 v[114:117], v[180:183], v[188:191], v[114:117]
	v_mfma_f32_16x16x32_bf16 v[106:109], v[172:175], v[204:207], v[106:109]
	v_mfma_f32_16x16x32_bf16 v[98:101], v[180:183], v[204:207], v[98:101]
	v_mfma_f32_16x16x32_bf16 v[90:93], v[172:175], v[212:215], v[90:93]
	v_mfma_f32_16x16x32_bf16 v[82:85], v[180:183], v[212:215], v[82:85]
	v_mfma_f32_16x16x32_bf16 v[74:77], v[172:175], v[220:223], v[74:77]
	v_mfma_f32_16x16x32_bf16 v[66:69], v[180:183], v[220:223], v[66:69]
	s_barrier
	s_setprio 0
	s_add_i32 s29, s29, s43
	s_mov_b32 m0, s29
	ds_read_b128 v[184:187], v155 offset:49152
	ds_read_b128 v[188:191], v155 offset:50176
	ds_read_b128 v[192:195], v155 offset:51200
	ds_read_b128 v[204:207], v155 offset:52224
	ds_read_b128 v[208:211], v155 offset:53248
	ds_read_b128 v[212:215], v155 offset:54272
	ds_read_b128 v[216:219], v155 offset:55296
	ds_read_b128 v[220:223], v155 offset:56320
	global_load_lds_dwordx4 v141, s[20:21]
	s_add_i32 m0, s29, 0x2000
	s_add_i32 s29, s30, s43
	global_load_lds_dwordx4 v153, s[20:21]
	s_add_u32 s20, s20, 0x40080
	s_addc_u32 s21, s21, 0
	s_mov_b32 m0, s29
	s_nop 0
	global_load_lds_dwordx4 v0, s[20:21]
	s_add_i32 m0, s29, 0x2000
	s_nop 0
	global_load_lds_dwordx4 v130, s[20:21]
	s_mov_b32 m0, s93
	s_nop 0
	global_load_lds_dwordx4 v201, s[56:57]
	s_mov_b32 m0, s44
	s_nop 0
	global_load_lds_dwordx4 v225, s[56:57]
	s_waitcnt vmcnt(8)
	s_waitcnt lgkmcnt(0)
	s_setprio 1
	s_barrier
	v_mfma_f32_16x16x32_bf16 v[62:65], v[146:149], v[184:187], v[62:65]
	v_mfma_f32_16x16x32_bf16 v[54:57], v[160:163], v[184:187], v[54:57]
	v_mfma_f32_16x16x32_bf16 v[46:49], v[146:149], v[192:195], v[46:49]
	v_mfma_f32_16x16x32_bf16 v[38:41], v[160:163], v[192:195], v[38:41]
	v_mfma_f32_16x16x32_bf16 v[30:33], v[146:149], v[208:211], v[30:33]
	v_mfma_f32_16x16x32_bf16 v[22:25], v[160:163], v[208:211], v[22:25]
	v_mfma_f32_16x16x32_bf16 v[14:17], v[146:149], v[216:219], v[14:17]
	v_mfma_f32_16x16x32_bf16 v[6:9], v[160:163], v[216:219], v[6:9]
	v_mfma_f32_16x16x32_bf16 v[62:65], v[156:159], v[188:191], v[62:65]
	v_mfma_f32_16x16x32_bf16 v[54:57], v[164:167], v[188:191], v[54:57]
	v_mfma_f32_16x16x32_bf16 v[46:49], v[156:159], v[204:207], v[46:49]
	v_mfma_f32_16x16x32_bf16 v[38:41], v[164:167], v[204:207], v[38:41]
	v_mfma_f32_16x16x32_bf16 v[30:33], v[156:159], v[212:215], v[30:33]
	v_mfma_f32_16x16x32_bf16 v[22:25], v[164:167], v[212:215], v[22:25]
	v_mfma_f32_16x16x32_bf16 v[14:17], v[156:159], v[220:223], v[14:17]
	v_mfma_f32_16x16x32_bf16 v[6:9], v[164:167], v[220:223], v[6:9]
	s_setprio 0
	s_setprio 1
	v_mfma_f32_16x16x32_bf16 v[58:61], v[168:171], v[184:187], v[58:61]
	v_mfma_f32_16x16x32_bf16 v[50:53], v[176:179], v[184:187], v[50:53]
	v_mfma_f32_16x16x32_bf16 v[42:45], v[168:171], v[192:195], v[42:45]
	v_mfma_f32_16x16x32_bf16 v[34:37], v[176:179], v[192:195], v[34:37]
	v_mfma_f32_16x16x32_bf16 v[26:29], v[168:171], v[208:211], v[26:29]
	v_mfma_f32_16x16x32_bf16 v[18:21], v[176:179], v[208:211], v[18:21]
	v_mfma_f32_16x16x32_bf16 v[10:13], v[168:171], v[216:219], v[10:13]
	v_mfma_f32_16x16x32_bf16 v[2:5], v[176:179], v[216:219], v[2:5]
	v_mfma_f32_16x16x32_bf16 v[58:61], v[172:175], v[188:191], v[58:61]
	v_mfma_f32_16x16x32_bf16 v[50:53], v[180:183], v[188:191], v[50:53]
	v_mfma_f32_16x16x32_bf16 v[42:45], v[172:175], v[204:207], v[42:45]
	v_mfma_f32_16x16x32_bf16 v[34:37], v[180:183], v[204:207], v[34:37]
	v_mfma_f32_16x16x32_bf16 v[26:29], v[172:175], v[212:215], v[26:29]
	v_mfma_f32_16x16x32_bf16 v[18:21], v[180:183], v[212:215], v[18:21]
	v_mfma_f32_16x16x32_bf16 v[10:13], v[172:175], v[220:223], v[10:13]
	v_mfma_f32_16x16x32_bf16 v[2:5], v[180:183], v[220:223], v[2:5]
	s_barrier
	s_setprio 0
	s_add_i32 s31, s31, 2
	s_add_u32 s23, s23, 0x100
	s_addc_u32 s24, s24, 0
	s_add_u32 s16, s16, 0x100
	s_addc_u32 s17, s17, 0
	s_cmp_gt_u32 s31, 13
	s_cbranch_scc0 .LBB0_369
	s_and_b64 vcc, exec, s[6:7]
	s_cbranch_vccz .LBB0_372
	s_barrier

; #define PG8_STAGE(bufoff, gbase, voff) do { _Pragma("unroll") for (int _i = 0; _i < 2; ++_i) \
;         __builtin_amdgcn_global_load_lds((const gunsigned*)((const gchar*)(gbase) + (voff)[_i]), (LAS unsigned*)(lds + (bufoff) + ldsw + _i * 8192), 16, 0, 0); } while (0)
; #define PG8_LDA(dst, b, h) do { _Pragma("unroll") for (int m = 0; m < 4; ++m) _Pragma("unroll") for (int k = 0; k < 2; ++k) dst[m][k] = *(const LAS bf16x8*)(lds + PG8_SA(b, h) + aoff + m * 2048 + k * 1024); } while (0)
; #define PG8_LDB(dst, b, h) do { _Pragma("unroll") for (int n = 0; n < 2; ++n) _Pragma("unroll") for (int k = 0; k < 2; ++k) dst[n][k] = *(const LAS bf16x8*)(lds + PG8_SB(b, h) + boff + n * 2048 + k * 1024); } while (0)
; #define PG8_MMA(ai, bj, At, Bt) do { __builtin_amdgcn_s_setprio(1); _Pragma("unroll") for (int m = 0; m < 4; ++m) _Pragma("unroll") for (int n = 0; n < 2; ++n) _Pragma("unroll") for (int k = 0; k < 2; ++k) \
;         acc[ai][bj][m][n] = __builtin_amdgcn_mfma_f32_16x16x32_bf16(Bt[n][k], At[m][k], acc[ai][bj][m][n], 0, 0, 0); __builtin_amdgcn_s_setprio(0); } while (0)
; #define PG8_WAIT_V(n) asm volatile("s_waitcnt vmcnt(" #n ")" ::: "memory")
; #define PG8_WAIT_L(n) asm volatile("s_waitcnt lgkmcnt(" #n ")" ::: "memory")
; #define PG8_BAR __builtin_amdgcn_s_barrier()
; #define PG8_SCHED __builtin_amdgcn_sched_barrier(0)
; template <class Epi, class Sched>
; __device__ __forceinline__ void gemm_phase(LAS unsigned char* lds, const int tid, const Gemm g, const Sched& S, const Epi& E) {
;     ...
;         for (int t = 0; t < nt; t += 2) {
;             const bool last = (t == nt - 2);
;             const gchar* a1 = cA + (size_t)(t + 1) * kstep;
;             const gchar* a2 = last ? nA : cA + (size_t)(t + 2) * kstep; const gchar* b2 = last ? nB : cB + (size_t)(t + 2) * kstep;
;             const gchar* a3 = a2 + kstep; const gchar* b3 = b2 + kstep;
;             PG8_LDB(B0, 0, 0); PG8_LDB(B1, 0, 1); PG8_SCHED; PG8_LDA(At, 0, 0); PG8_STAGE(PG8_SA(1, 1), a1 + hstep, voffA);
;             PG8_WAIT_V(8); PG8_WAIT_L(0); PG8_BAR; PG8_MMA(0, 0, At, B0); PG8_MMA(0, 1, At, B1); PG8_BAR; PG8_SCHED;
;             PG8_LDA(At, 0, 1); PG8_STAGE(PG8_SB(0, 0), b2, voffB); PG8_STAGE(PG8_SB(0, 1), b2 + hstep, voffB); PG8_STAGE(PG8_SA(0, 0), a2, voffA);
;             PG8_WAIT_V(8); PG8_WAIT_L(0); PG8_BAR; PG8_MMA(1, 0, At, B0); PG8_MMA(1, 1, At, B1); PG8_BAR; PG8_SCHED;
.LBB0_397:
	s_add_u32 s20, s92, 0xfffc0080
	s_addc_u32 s21, s93, -1
	s_add_i32 s29, 0, 0x10000
	s_cmp_eq_u32 s53, 12
	s_cselect_b32 s73, s1, s21
	s_cselect_b32 s72, s31, s20
	s_cselect_b32 s21, s17, s52
	s_cselect_b32 s20, s50, s51
	s_add_i32 s30, 0, 0x14000
	v_add_u32_e32 v142, s29, v177
	v_add_u32_e32 v168, s30, v177
	ds_read_b128 v[130:133], v142
	ds_read_b128 v[134:137], v142 offset:1024
	ds_read_b128 v[138:141], v142 offset:2048
	ds_read_b128 v[142:145], v142 offset:3072
	ds_read_b128 v[146:149], v168
	ds_read_b128 v[150:153], v168 offset:1024
	ds_read_b128 v[164:167], v168 offset:2048
	ds_read_b128 v[168:171], v168 offset:3072
	s_add_i32 m0, s43, 0xc000
	ds_read_b128 v[172:175], v181
	ds_read_b128 v[182:185], v181 offset:1024
	ds_read_b128 v[186:189], v181 offset:2048
	ds_read_b128 v[190:193], v181 offset:3072
	ds_read_b128 v[204:207], v181 offset:4096
	ds_read_b128 v[208:211], v181 offset:5120
	ds_read_b128 v[212:215], v181 offset:6144
	ds_read_b128 v[216:219], v181 offset:7168
	global_load_lds_dwordx4 v162, s[92:93]
	s_add_i32 m0, s43, 0xe000
	s_nop 0
	global_load_lds_dwordx4 v160, s[92:93]
	s_waitcnt vmcnt(8)
	s_waitcnt lgkmcnt(0)
	s_setprio 1
	s_barrier
	v_mfma_f32_16x16x32_bf16 v[126:129], v[130:133], v[172:175], v[126:129]
	v_mfma_f32_16x16x32_bf16 v[122:125], v[138:141], v[172:175], v[122:125]
	v_mfma_f32_16x16x32_bf16 v[110:113], v[130:133], v[186:189], v[110:113]
	v_mfma_f32_16x16x32_bf16 v[106:109], v[138:141], v[186:189], v[106:109]
	v_mfma_f32_16x16x32_bf16 v[94:97], v[130:133], v[204:207], v[94:97]
	v_mfma_f32_16x16x32_bf16 v[90:93], v[138:141], v[204:207], v[90:93]
	v_mfma_f32_16x16x32_bf16 v[78:81], v[130:133], v[212:215], v[78:81]
	v_mfma_f32_16x16x32_bf16 v[74:77], v[138:141], v[212:215], v[74:77]
	v_mfma_f32_16x16x32_bf16 v[126:129], v[134:137], v[182:185], v[126:129]
	v_mfma_f32_16x16x32_bf16 v[122:125], v[142:145], v[182:185], v[122:125]
	v_mfma_f32_16x16x32_bf16 v[110:113], v[134:137], v[190:193], v[110:113]
	v_mfma_f32_16x16x32_bf16 v[106:109], v[142:145], v[190:193], v[106:109]
	v_mfma_f32_16x16x32_bf16 v[94:97], v[134:137], v[208:211], v[94:97]
	v_mfma_f32_16x16x32_bf16 v[90:93], v[142:145], v[208:211], v[90:93]
	v_mfma_f32_16x16x32_bf16 v[78:81], v[134:137], v[216:219], v[78:81]
	v_mfma_f32_16x16x32_bf16 v[74:77], v[142:145], v[216:219], v[74:77]
	s_setprio 0
	s_setprio 1
	v_mfma_f32_16x16x32_bf16 v[118:121], v[146:149], v[172:175], v[118:121]
	v_mfma_f32_16x16x32_bf16 v[114:117], v[164:167], v[172:175], v[114:117]
	v_mfma_f32_16x16x32_bf16 v[102:105], v[146:149], v[186:189], v[102:105]
	v_mfma_f32_16x16x32_bf16 v[98:101], v[164:167], v[186:189], v[98:101]
	v_mfma_f32_16x16x32_bf16 v[86:89], v[146:149], v[204:207], v[86:89]
	v_mfma_f32_16x16x32_bf16 v[82:85], v[164:167], v[204:207], v[82:85]
	v_mfma_f32_16x16x32_bf16 v[70:73], v[146:149], v[212:215], v[70:73]
	v_mfma_f32_16x16x32_bf16 v[66:69], v[164:167], v[212:215], v[66:69]
	v_mfma_f32_16x16x32_bf16 v[118:121], v[150:153], v[182:185], v[118:121]
	v_mfma_f32_16x16x32_bf16 v[114:117], v[168:171], v[182:185], v[114:117]
	v_mfma_f32_16x16x32_bf16 v[102:105], v[150:153], v[190:193], v[102:105]
	v_mfma_f32_16x16x32_bf16 v[98:101], v[168:171], v[190:193], v[98:101]
	v_mfma_f32_16x16x32_bf16 v[86:89], v[150:153], v[208:211], v[86:89]
	v_mfma_f32_16x16x32_bf16 v[82:85], v[168:171], v[208:211], v[82:85]
	v_mfma_f32_16x16x32_bf16 v[70:73], v[150:153], v[216:219], v[70:73]
	v_mfma_f32_16x16x32_bf16 v[66:69], v[168:171], v[216:219], v[66:69]
	s_barrier
	s_setprio 0
	s_add_i32 s29, s29, s15
	s_mov_b32 m0, s29
	ds_read_b128 v[172:175], v181 offset:16384
	ds_read_b128 v[182:185], v181 offset:17408
	ds_read_b128 v[186:189], v181 offset:18432
	ds_read_b128 v[190:193], v181 offset:19456
	ds_read_b128 v[204:207], v181 offset:20480
	ds_read_b128 v[208:211], v181 offset:21504
	ds_read_b128 v[212:215], v181 offset:22528
	ds_read_b128 v[216:219], v181 offset:23552
	global_load_lds_dwordx4 v0, s[20:21]
	s_add_i32 m0, s29, 0x2000
	s_add_u32 s54, s20, 0x40000
	s_addc_u32 s55, s21, 0
	s_add_i32 s29, s30, s15
	global_load_lds_dwordx4 v158, s[20:21]
	s_mov_b32 m0, s29
	s_nop 0
	global_load_lds_dwordx4 v0, s[54:55]
	s_add_i32 m0, s29, 0x2000
	s_nop 0
	global_load_lds_dwordx4 v158, s[54:55]
	s_mov_b32 m0, s43
	s_nop 0
	global_load_lds_dwordx4 v154, s[72:73]
	s_mov_b32 m0, s44
	s_nop 0
	global_load_lds_dwordx4 v156, s[72:73]
	s_waitcnt vmcnt(8)
	s_waitcnt lgkmcnt(0)
	s_setprio 1
	s_barrier
	v_mfma_f32_16x16x32_bf16 v[62:65], v[130:133], v[172:175], v[62:65]
	v_mfma_f32_16x16x32_bf16 v[58:61], v[138:141], v[172:175], v[58:61]
	v_mfma_f32_16x16x32_bf16 v[46:49], v[130:133], v[186:189], v[46:49]
	v_mfma_f32_16x16x32_bf16 v[42:45], v[138:141], v[186:189], v[42:45]
	v_mfma_f32_16x16x32_bf16 v[30:33], v[130:133], v[204:207], v[30:33]
	v_mfma_f32_16x16x32_bf16 v[26:29], v[138:141], v[204:207], v[26:29]
	v_mfma_f32_16x16x32_bf16 v[14:17], v[130:133], v[212:215], v[14:17]
	v_mfma_f32_16x16x32_bf16 v[10:13], v[138:141], v[212:215], v[10:13]
	v_mfma_f32_16x16x32_bf16 v[62:65], v[134:137], v[182:185], v[62:65]
	v_mfma_f32_16x16x32_bf16 v[58:61], v[142:145], v[182:185], v[58:61]
	v_mfma_f32_16x16x32_bf16 v[46:49], v[134:137], v[190:193], v[46:49]
	v_mfma_f32_16x16x32_bf16 v[42:45], v[142:145], v[190:193], v[42:45]
	v_mfma_f32_16x16x32_bf16 v[30:33], v[134:137], v[208:211], v[30:33]
	v_mfma_f32_16x16x32_bf16 v[26:29], v[142:145], v[208:211], v[26:29]
	v_mfma_f32_16x16x32_bf16 v[14:17], v[134:137], v[216:219], v[14:17]
	v_mfma_f32_16x16x32_bf16 v[10:13], v[142:145], v[216:219], v[10:13]
	s_setprio 0
	s_setprio 1
	v_mfma_f32_16x16x32_bf16 v[54:57], v[146:149], v[172:175], v[54:57]
	v_mfma_f32_16x16x32_bf16 v[50:53], v[164:167], v[172:175], v[50:53]
	v_mfma_f32_16x16x32_bf16 v[38:41], v[146:149], v[186:189], v[38:41]
	v_mfma_f32_16x16x32_bf16 v[34:37], v[164:167], v[186:189], v[34:37]
	v_mfma_f32_16x16x32_bf16 v[22:25], v[146:149], v[204:207], v[22:25]
	v_mfma_f32_16x16x32_bf16 v[18:21], v[164:167], v[204:207], v[18:21]
	v_mfma_f32_16x16x32_bf16 v[6:9], v[146:149], v[212:215], v[6:9]
	v_mfma_f32_16x16x32_bf16 v[2:5], v[164:167], v[212:215], v[2:5]
	v_mfma_f32_16x16x32_bf16 v[54:57], v[150:153], v[182:185], v[54:57]
	v_mfma_f32_16x16x32_bf16 v[50:53], v[168:171], v[182:185], v[50:53]
	v_mfma_f32_16x16x32_bf16 v[38:41], v[150:153], v[190:193], v[38:41]
	v_mfma_f32_16x16x32_bf16 v[34:37], v[168:171], v[190:193], v[34:37]
	v_mfma_f32_16x16x32_bf16 v[22:25], v[150:153], v[208:211], v[22:25]
	v_mfma_f32_16x16x32_bf16 v[18:21], v[168:171], v[208:211], v[18:21]
	v_mfma_f32_16x16x32_bf16 v[6:9], v[150:153], v[216:219], v[6:9]
	v_mfma_f32_16x16x32_bf16 v[2:5], v[168:171], v[216:219], v[2:5]
	s_barrier
; #define PG8_STAGE(bufoff, gbase, voff) do { _Pragma("unroll") for (int _i = 0; _i < 2; ++_i) \
;         __builtin_amdgcn_global_load_lds((const gunsigned*)((const gchar*)(gbase) + (voff)[_i]), (LAS unsigned*)(lds + (bufoff) + ldsw + _i * 8192), 16, 0, 0); } while (0)
; #define PG8_LDA(dst, b, h) do { _Pragma("unroll") for (int m = 0; m < 4; ++m) _Pragma("unroll") for (int k = 0; k < 2; ++k) dst[m][k] = *(const LAS bf16x8*)(lds + PG8_SA(b, h) + aoff + m * 2048 + k * 1024); } while (0)
; #define PG8_LDB(dst, b, h) do { _Pragma("unroll") for (int n = 0; n < 2; ++n) _Pragma("unroll") for (int k = 0; k < 2; ++k) dst[n][k] = *(const LAS bf16x8*)(lds + PG8_SB(b, h) + boff + n * 2048 + k * 1024); } while (0)
; #define PG8_MMA(ai, bj, At, Bt) do { __builtin_amdgcn_s_setprio(1); _Pragma("unroll") for (int m = 0; m < 4; ++m) _Pragma("unroll") for (int n = 0; n < 2; ++n) _Pragma("unroll") for (int k = 0; k < 2; ++k) \
;         acc[ai][bj][m][n] = __builtin_amdgcn_mfma_f32_16x16x32_bf16(Bt[n][k], At[m][k], acc[ai][bj][m][n], 0, 0, 0); __builtin_amdgcn_s_setprio(0); } while (0)
; #define PG8_WAIT_V(n) asm volatile("s_waitcnt vmcnt(" #n ")" ::: "memory")
; #define PG8_WAIT_L(n) asm volatile("s_waitcnt lgkmcnt(" #n ")" ::: "memory")
; #define PG8_BAR __builtin_amdgcn_s_barrier()
; #define PG8_SCHED __builtin_amdgcn_sched_barrier(0)
; template <class Epi, class Sched>
; __device__ __forceinline__ void gemm_phase(LAS unsigned char* lds, const int tid, const Gemm g, const Sched& S, const Epi& E) {
;     ...
;             PG8_LDB(B0, 1, 0); PG8_LDB(B1, 1, 1); PG8_SCHED; PG8_LDA(At, 1, 0); PG8_STAGE(PG8_SA(0, 1), a2 + hstep, voffA);
;             PG8_WAIT_V(8); PG8_WAIT_L(0); PG8_BAR; PG8_MMA(0, 0, At, B0); PG8_MMA(0, 1, At, B1); PG8_BAR; PG8_SCHED;
;             PG8_LDA(At, 1, 1); PG8_STAGE(PG8_SB(1, 0), b3, voffB); PG8_STAGE(PG8_SB(1, 1), b3 + hstep, voffB); PG8_STAGE(PG8_SA(1, 0), a3, voffA);
;             PG8_WAIT_V(8); PG8_WAIT_L(0); PG8_BAR; PG8_MMA(1, 0, At, B0); PG8_MMA(1, 1, At, B1); PG8_BAR; PG8_SCHED;
;         }
;         if (wr == 0) PG8_BAR;
	s_setprio 0
	s_add_i32 s29, 0, 0x18000
	s_add_i32 s30, 0, 0x1c000
	v_add_u32_e32 v142, s29, v177
	v_add_u32_e32 v168, s30, v177
	ds_read_b128 v[130:133], v142
	ds_read_b128 v[134:137], v142 offset:1024
	ds_read_b128 v[138:141], v142 offset:2048
	ds_read_b128 v[142:145], v142 offset:3072
	ds_read_b128 v[146:149], v168
	ds_read_b128 v[150:153], v168 offset:1024
	ds_read_b128 v[164:167], v168 offset:2048
	ds_read_b128 v[168:171], v168 offset:3072
	s_add_u32 s54, s72, 0x40000
	s_addc_u32 s55, s73, 0
	s_mov_b32 m0, s45
	ds_read_b128 v[172:175], v181 offset:32768
	ds_read_b128 v[182:185], v181 offset:33792
	ds_read_b128 v[186:189], v181 offset:34816
	ds_read_b128 v[190:193], v181 offset:35840
	ds_read_b128 v[204:207], v181 offset:36864
	ds_read_b128 v[208:211], v181 offset:37888
	ds_read_b128 v[212:215], v181 offset:38912
	ds_read_b128 v[216:219], v181 offset:39936
	global_load_lds_dwordx4 v154, s[54:55]
	s_mov_b32 m0, s46
	s_nop 0
	global_load_lds_dwordx4 v156, s[54:55]
	s_waitcnt vmcnt(8)
	s_waitcnt lgkmcnt(0)
	s_setprio 1
	s_barrier
	v_mfma_f32_16x16x32_bf16 v[126:129], v[130:133], v[172:175], v[126:129]
	v_mfma_f32_16x16x32_bf16 v[122:125], v[138:141], v[172:175], v[122:125]
	v_mfma_f32_16x16x32_bf16 v[110:113], v[130:133], v[186:189], v[110:113]
	v_mfma_f32_16x16x32_bf16 v[106:109], v[138:141], v[186:189], v[106:109]
	v_mfma_f32_16x16x32_bf16 v[94:97], v[130:133], v[204:207], v[94:97]
	v_mfma_f32_16x16x32_bf16 v[90:93], v[138:141], v[204:207], v[90:93]
	v_mfma_f32_16x16x32_bf16 v[78:81], v[130:133], v[212:215], v[78:81]
	v_mfma_f32_16x16x32_bf16 v[74:77], v[138:141], v[212:215], v[74:77]
	v_mfma_f32_16x16x32_bf16 v[126:129], v[134:137], v[182:185], v[126:129]
	v_mfma_f32_16x16x32_bf16 v[122:125], v[142:145], v[182:185], v[122:125]
	v_mfma_f32_16x16x32_bf16 v[110:113], v[134:137], v[190:193], v[110:113]
	v_mfma_f32_16x16x32_bf16 v[106:109], v[142:145], v[190:193], v[106:109]
	v_mfma_f32_16x16x32_bf16 v[94:97], v[134:137], v[208:211], v[94:97]
	v_mfma_f32_16x16x32_bf16 v[90:93], v[142:145], v[208:211], v[90:93]
	v_mfma_f32_16x16x32_bf16 v[78:81], v[134:137], v[216:219], v[78:81]
	v_mfma_f32_16x16x32_bf16 v[74:77], v[142:145], v[216:219], v[74:77]
	s_setprio 0
	s_setprio 1
	v_mfma_f32_16x16x32_bf16 v[118:121], v[146:149], v[172:175], v[118:121]
	v_mfma_f32_16x16x32_bf16 v[114:117], v[164:167], v[172:175], v[114:117]
	v_mfma_f32_16x16x32_bf16 v[102:105], v[146:149], v[186:189], v[102:105]
	v_mfma_f32_16x16x32_bf16 v[98:101], v[164:167], v[186:189], v[98:101]
	v_mfma_f32_16x16x32_bf16 v[86:89], v[146:149], v[204:207], v[86:89]
	v_mfma_f32_16x16x32_bf16 v[82:85], v[164:167], v[204:207], v[82:85]
	v_mfma_f32_16x16x32_bf16 v[70:73], v[146:149], v[212:215], v[70:73]
	v_mfma_f32_16x16x32_bf16 v[66:69], v[164:167], v[212:215], v[66:69]
	v_mfma_f32_16x16x32_bf16 v[118:121], v[150:153], v[182:185], v[118:121]
	v_mfma_f32_16x16x32_bf16 v[114:117], v[168:171], v[182:185], v[114:117]
	v_mfma_f32_16x16x32_bf16 v[102:105], v[150:153], v[190:193], v[102:105]
	v_mfma_f32_16x16x32_bf16 v[98:101], v[168:171], v[190:193], v[98:101]
	v_mfma_f32_16x16x32_bf16 v[86:89], v[150:153], v[208:211], v[86:89]
	v_mfma_f32_16x16x32_bf16 v[82:85], v[168:171], v[208:211], v[82:85]
	v_mfma_f32_16x16x32_bf16 v[70:73], v[150:153], v[216:219], v[70:73]
	v_mfma_f32_16x16x32_bf16 v[66:69], v[168:171], v[216:219], v[66:69]
	s_barrier
	s_setprio 0
	s_add_i32 s29, s29, s15
	s_mov_b32 m0, s29
	ds_read_b128 v[172:175], v181 offset:49152
	ds_read_b128 v[182:185], v181 offset:50176
	ds_read_b128 v[186:189], v181 offset:51200
	ds_read_b128 v[190:193], v181 offset:52224
	ds_read_b128 v[204:207], v181 offset:53248
	ds_read_b128 v[208:211], v181 offset:54272
	ds_read_b128 v[212:215], v181 offset:55296
	ds_read_b128 v[216:219], v181 offset:56320
	global_load_lds_dwordx4 v195, s[20:21]
	s_add_i32 m0, s29, 0x2000
	s_add_i32 s29, s30, s15
	global_load_lds_dwordx4 v201, s[20:21]
	s_add_u32 s20, s20, 0x40080
	s_addc_u32 s21, s21, 0
	s_mov_b32 m0, s29
	s_nop 0
	global_load_lds_dwordx4 v0, s[20:21]
	s_add_i32 m0, s29, 0x2000
	s_nop 0
	global_load_lds_dwordx4 v158, s[20:21]
	s_mov_b32 m0, s12
	s_nop 0
	global_load_lds_dwordx4 v221, s[72:73]
	s_mov_b32 m0, s47
	s_nop 0
	global_load_lds_dwordx4 v223, s[72:73]
	s_waitcnt vmcnt(8)
	s_waitcnt lgkmcnt(0)
	s_setprio 1
	s_barrier
	v_mfma_f32_16x16x32_bf16 v[62:65], v[130:133], v[172:175], v[62:65]
	v_mfma_f32_16x16x32_bf16 v[58:61], v[138:141], v[172:175], v[58:61]
	v_mfma_f32_16x16x32_bf16 v[46:49], v[130:133], v[186:189], v[46:49]
	v_mfma_f32_16x16x32_bf16 v[42:45], v[138:141], v[186:189], v[42:45]
	v_mfma_f32_16x16x32_bf16 v[30:33], v[130:133], v[204:207], v[30:33]
	v_mfma_f32_16x16x32_bf16 v[26:29], v[138:141], v[204:207], v[26:29]
	v_mfma_f32_16x16x32_bf16 v[14:17], v[130:133], v[212:215], v[14:17]
	v_mfma_f32_16x16x32_bf16 v[10:13], v[138:141], v[212:215], v[10:13]
	v_mfma_f32_16x16x32_bf16 v[62:65], v[134:137], v[182:185], v[62:65]
	v_mfma_f32_16x16x32_bf16 v[58:61], v[142:145], v[182:185], v[58:61]
	v_mfma_f32_16x16x32_bf16 v[46:49], v[134:137], v[190:193], v[46:49]
	v_mfma_f32_16x16x32_bf16 v[42:45], v[142:145], v[190:193], v[42:45]
	v_mfma_f32_16x16x32_bf16 v[30:33], v[134:137], v[208:211], v[30:33]
	v_mfma_f32_16x16x32_bf16 v[26:29], v[142:145], v[208:211], v[26:29]
	v_mfma_f32_16x16x32_bf16 v[14:17], v[134:137], v[216:219], v[14:17]
	v_mfma_f32_16x16x32_bf16 v[10:13], v[142:145], v[216:219], v[10:13]
	s_setprio 0
	s_setprio 1
	v_mfma_f32_16x16x32_bf16 v[54:57], v[146:149], v[172:175], v[54:57]
	v_mfma_f32_16x16x32_bf16 v[50:53], v[164:167], v[172:175], v[50:53]
	v_mfma_f32_16x16x32_bf16 v[38:41], v[146:149], v[186:189], v[38:41]
	v_mfma_f32_16x16x32_bf16 v[34:37], v[164:167], v[186:189], v[34:37]
	v_mfma_f32_16x16x32_bf16 v[22:25], v[146:149], v[204:207], v[22:25]
	v_mfma_f32_16x16x32_bf16 v[18:21], v[164:167], v[204:207], v[18:21]
	v_mfma_f32_16x16x32_bf16 v[6:9], v[146:149], v[212:215], v[6:9]
	v_mfma_f32_16x16x32_bf16 v[2:5], v[164:167], v[212:215], v[2:5]
	v_mfma_f32_16x16x32_bf16 v[54:57], v[150:153], v[182:185], v[54:57]
	v_mfma_f32_16x16x32_bf16 v[50:53], v[168:171], v[182:185], v[50:53]
	v_mfma_f32_16x16x32_bf16 v[38:41], v[150:153], v[190:193], v[38:41]
	v_mfma_f32_16x16x32_bf16 v[34:37], v[168:171], v[190:193], v[34:37]
	v_mfma_f32_16x16x32_bf16 v[22:25], v[150:153], v[208:211], v[22:25]
	v_mfma_f32_16x16x32_bf16 v[18:21], v[168:171], v[208:211], v[18:21]
	v_mfma_f32_16x16x32_bf16 v[6:9], v[150:153], v[216:219], v[6:9]
	v_mfma_f32_16x16x32_bf16 v[2:5], v[168:171], v[216:219], v[2:5]
	s_barrier
	s_setprio 0
	s_add_i32 s53, s53, 2
	s_add_u32 s51, s51, 0x100
	s_addc_u32 s52, s52, 0
	s_add_u32 s92, s92, 0x100
	s_addc_u32 s93, s93, 0
	s_cmp_gt_u32 s53, 13
	s_cbranch_scc0 .LBB0_397
	s_and_b64 vcc, exec, s[10:11]
	s_cbranch_vccz .LBB0_400
	s_barrier

; #define PG8_STAGE(bufoff, gbase, voff) do { _Pragma("unroll") for (int _i = 0; _i < 2; ++_i) \
;         __builtin_amdgcn_global_load_lds((const gunsigned*)((const gchar*)(gbase) + (voff)[_i]), (LAS unsigned*)(lds + (bufoff) + ldsw + _i * 8192), 16, 0, 0); } while (0)
; #define PG8_LDA(dst, b, h) do { _Pragma("unroll") for (int m = 0; m < 4; ++m) _Pragma("unroll") for (int k = 0; k < 2; ++k) dst[m][k] = *(const LAS bf16x8*)(lds + PG8_SA(b, h) + aoff + m * 2048 + k * 1024); } while (0)
; #define PG8_LDB(dst, b, h) do { _Pragma("unroll") for (int n = 0; n < 2; ++n) _Pragma("unroll") for (int k = 0; k < 2; ++k) dst[n][k] = *(const LAS bf16x8*)(lds + PG8_SB(b, h) + boff + n * 2048 + k * 1024); } while (0)
; #define PG8_MMA(ai, bj, At, Bt) do { __builtin_amdgcn_s_setprio(1); _Pragma("unroll") for (int m = 0; m < 4; ++m) _Pragma("unroll") for (int n = 0; n < 2; ++n) _Pragma("unroll") for (int k = 0; k < 2; ++k) \
;         acc[ai][bj][m][n] = __builtin_amdgcn_mfma_f32_16x16x32_bf16(Bt[n][k], At[m][k], acc[ai][bj][m][n], 0, 0, 0); __builtin_amdgcn_s_setprio(0); } while (0)
; #define PG8_WAIT_V(n) asm volatile("s_waitcnt vmcnt(" #n ")" ::: "memory")
; #define PG8_WAIT_L(n) asm volatile("s_waitcnt lgkmcnt(" #n ")" ::: "memory")
; #define PG8_BAR __builtin_amdgcn_s_barrier()
; #define PG8_SCHED __builtin_amdgcn_sched_barrier(0)
; template <class Epi, class Sched>
; __device__ __forceinline__ void gemm_phase(LAS unsigned char* lds, const int tid, const Gemm g, const Sched& S, const Epi& E) {
;     ...
;         for (int t = 0; t < nt; t += 2) {
;             const bool last = (t == nt - 2);
;             const gchar* a1 = cA + (size_t)(t + 1) * kstep;
;             const gchar* a2 = last ? nA : cA + (size_t)(t + 2) * kstep; const gchar* b2 = last ? nB : cB + (size_t)(t + 2) * kstep;
;             const gchar* a3 = a2 + kstep; const gchar* b3 = b2 + kstep;
;             PG8_LDB(B0, 0, 0); PG8_LDB(B1, 0, 1); PG8_SCHED; PG8_LDA(At, 0, 0); PG8_STAGE(PG8_SA(1, 1), a1 + hstep, voffA);
;             PG8_WAIT_V(8); PG8_WAIT_L(0); PG8_BAR; PG8_MMA(0, 0, At, B0); PG8_MMA(0, 1, At, B1); PG8_BAR; PG8_SCHED;
;             PG8_LDA(At, 0, 1); PG8_STAGE(PG8_SB(0, 0), b2, voffB); PG8_STAGE(PG8_SB(0, 1), b2 + hstep, voffB); PG8_STAGE(PG8_SA(0, 0), a2, voffA);
;             PG8_WAIT_V(8); PG8_WAIT_L(0); PG8_BAR; PG8_MMA(1, 0, At, B0); PG8_MMA(1, 1, At, B1); PG8_BAR; PG8_SCHED;
.LBB0_444:
	s_add_u32 s20, s16, 0xfffe0080
	s_addc_u32 s21, s17, -1
	s_add_i32 s29, 0, 0x10000
	s_cmp_eq_u32 s51, 4
	s_cselect_b32 s73, s1, s21
	s_cselect_b32 s72, s5, s20
	v_add_u32_e32 v122, s29, v242
	s_cselect_b32 s21, s15, s31
	s_cselect_b32 s20, s23, s24
	s_add_i32 s30, 0, 0x14000
	ds_read_b128 v[132:135], v122
	ds_read_b128 v[136:139], v122 offset:1024
	ds_read_b128 v[140:143], v122 offset:2048
	ds_read_b128 v[144:147], v122 offset:3072
	v_add_u32_e32 v122, s30, v242
	ds_read_b128 v[148:151], v122
	ds_read_b128 v[152:155], v122 offset:1024
	ds_read_b128 v[156:159], v122 offset:2048
	ds_read_b128 v[160:163], v122 offset:3072
	s_add_i32 m0, s93, 0xc000
	ds_read_b128 v[164:167], v244
	ds_read_b128 v[168:171], v244 offset:1024
	ds_read_b128 v[172:175], v244 offset:2048
	ds_read_b128 v[176:179], v244 offset:3072
	ds_read_b128 v[180:183], v244 offset:4096
	ds_read_b128 v[184:187], v244 offset:5120
	ds_read_b128 v[188:191], v244 offset:6144
	ds_read_b128 v[192:195], v244 offset:7168
	global_load_lds_dwordx4 v212, s[16:17]
	s_add_i32 m0, s93, 0xe000
	s_nop 0
	global_load_lds_dwordx4 v210, s[16:17]
	s_waitcnt vmcnt(8)
	s_waitcnt lgkmcnt(0)
	s_setprio 1
	s_barrier
	v_mfma_f32_16x16x32_bf16 v[128:131], v[132:135], v[164:167], v[128:131]
	v_mfma_f32_16x16x32_bf16 v[122:125], v[140:143], v[164:167], v[124:127]
	v_mfma_f32_16x16x32_bf16 v[110:113], v[132:135], v[172:175], v[110:113]
	v_mfma_f32_16x16x32_bf16 v[106:109], v[140:143], v[172:175], v[106:109]
	v_mfma_f32_16x16x32_bf16 v[94:97], v[132:135], v[180:183], v[94:97]
	v_mfma_f32_16x16x32_bf16 v[90:93], v[140:143], v[180:183], v[90:93]
	v_mfma_f32_16x16x32_bf16 v[78:81], v[132:135], v[188:191], v[78:81]
	v_mfma_f32_16x16x32_bf16 v[74:77], v[140:143], v[188:191], v[74:77]
	v_mfma_f32_16x16x32_bf16 v[128:131], v[136:139], v[168:171], v[128:131]
	v_mfma_f32_16x16x32_bf16 v[122:125], v[144:147], v[168:171], v[122:125]
	v_mfma_f32_16x16x32_bf16 v[110:113], v[136:139], v[176:179], v[110:113]
	v_mfma_f32_16x16x32_bf16 v[106:109], v[144:147], v[176:179], v[106:109]
	v_mfma_f32_16x16x32_bf16 v[94:97], v[136:139], v[184:187], v[94:97]
	v_mfma_f32_16x16x32_bf16 v[90:93], v[144:147], v[184:187], v[90:93]
	v_mfma_f32_16x16x32_bf16 v[78:81], v[136:139], v[192:195], v[78:81]
	v_mfma_f32_16x16x32_bf16 v[74:77], v[144:147], v[192:195], v[74:77]
	s_setprio 0
	s_setprio 1
	v_mfma_f32_16x16x32_bf16 v[118:121], v[148:151], v[164:167], v[118:121]
	v_mfma_f32_16x16x32_bf16 v[114:117], v[156:159], v[164:167], v[114:117]
	v_mfma_f32_16x16x32_bf16 v[102:105], v[148:151], v[172:175], v[102:105]
	v_mfma_f32_16x16x32_bf16 v[98:101], v[156:159], v[172:175], v[98:101]
	v_mfma_f32_16x16x32_bf16 v[86:89], v[148:151], v[180:183], v[86:89]
	v_mfma_f32_16x16x32_bf16 v[82:85], v[156:159], v[180:183], v[82:85]
	v_mfma_f32_16x16x32_bf16 v[70:73], v[148:151], v[188:191], v[70:73]
	v_mfma_f32_16x16x32_bf16 v[66:69], v[156:159], v[188:191], v[66:69]
	v_mfma_f32_16x16x32_bf16 v[118:121], v[152:155], v[168:171], v[118:121]
	v_mfma_f32_16x16x32_bf16 v[114:117], v[160:163], v[168:171], v[114:117]
	v_mfma_f32_16x16x32_bf16 v[102:105], v[152:155], v[176:179], v[102:105]
	v_mfma_f32_16x16x32_bf16 v[98:101], v[160:163], v[176:179], v[98:101]
	v_mfma_f32_16x16x32_bf16 v[86:89], v[152:155], v[184:187], v[86:89]
	v_mfma_f32_16x16x32_bf16 v[82:85], v[160:163], v[184:187], v[82:85]
	v_mfma_f32_16x16x32_bf16 v[70:73], v[152:155], v[192:195], v[70:73]
	v_mfma_f32_16x16x32_bf16 v[66:69], v[160:163], v[192:195], v[66:69]
	s_barrier
	s_setprio 0
	s_add_i32 s29, s29, s42
	s_mov_b32 m0, s29
	ds_read_b128 v[164:167], v244 offset:16384
	ds_read_b128 v[168:171], v244 offset:17408
	ds_read_b128 v[172:175], v244 offset:18432
	ds_read_b128 v[176:179], v244 offset:19456
	ds_read_b128 v[180:183], v244 offset:20480
	ds_read_b128 v[184:187], v244 offset:21504
	ds_read_b128 v[188:191], v244 offset:22528
	ds_read_b128 v[192:195], v244 offset:23552
	global_load_lds_dwordx4 v0, s[20:21]
	s_add_i32 m0, s29, 0x2000
	s_add_u32 s52, s20, 0x20000
	s_addc_u32 s53, s21, 0
	s_add_i32 s29, s30, s42
	global_load_lds_dwordx4 v208, s[20:21]
	s_mov_b32 m0, s29
	s_nop 0
	global_load_lds_dwordx4 v0, s[52:53]
	s_add_i32 m0, s29, 0x2000
	s_nop 0
	global_load_lds_dwordx4 v208, s[52:53]
	s_mov_b32 m0, s93
	s_nop 0
	global_load_lds_dwordx4 v204, s[72:73]
	s_mov_b32 m0, s44
	s_nop 0
	global_load_lds_dwordx4 v206, s[72:73]
	s_waitcnt vmcnt(8)
	s_waitcnt lgkmcnt(0)
	s_setprio 1
	s_barrier
	v_mfma_f32_16x16x32_bf16 v[62:65], v[132:135], v[164:167], v[62:65]
	v_mfma_f32_16x16x32_bf16 v[58:61], v[140:143], v[164:167], v[58:61]
	v_mfma_f32_16x16x32_bf16 v[46:49], v[132:135], v[172:175], v[46:49]
	v_mfma_f32_16x16x32_bf16 v[42:45], v[140:143], v[172:175], v[42:45]
	v_mfma_f32_16x16x32_bf16 v[30:33], v[132:135], v[180:183], v[30:33]
	v_mfma_f32_16x16x32_bf16 v[26:29], v[140:143], v[180:183], v[26:29]
	v_mfma_f32_16x16x32_bf16 v[14:17], v[132:135], v[188:191], v[14:17]
	v_mfma_f32_16x16x32_bf16 v[10:13], v[140:143], v[188:191], v[10:13]
	v_mfma_f32_16x16x32_bf16 v[62:65], v[136:139], v[168:171], v[62:65]
	v_mfma_f32_16x16x32_bf16 v[58:61], v[144:147], v[168:171], v[58:61]
	v_mfma_f32_16x16x32_bf16 v[46:49], v[136:139], v[176:179], v[46:49]
	v_mfma_f32_16x16x32_bf16 v[42:45], v[144:147], v[176:179], v[42:45]
	v_mfma_f32_16x16x32_bf16 v[30:33], v[136:139], v[184:187], v[30:33]
	v_mfma_f32_16x16x32_bf16 v[26:29], v[144:147], v[184:187], v[26:29]
	v_mfma_f32_16x16x32_bf16 v[14:17], v[136:139], v[192:195], v[14:17]
	v_mfma_f32_16x16x32_bf16 v[10:13], v[144:147], v[192:195], v[10:13]
	s_setprio 0
	s_setprio 1
	v_mfma_f32_16x16x32_bf16 v[54:57], v[148:151], v[164:167], v[54:57]
	v_mfma_f32_16x16x32_bf16 v[50:53], v[156:159], v[164:167], v[50:53]
	v_mfma_f32_16x16x32_bf16 v[38:41], v[148:151], v[172:175], v[38:41]
	v_mfma_f32_16x16x32_bf16 v[34:37], v[156:159], v[172:175], v[34:37]
	v_mfma_f32_16x16x32_bf16 v[22:25], v[148:151], v[180:183], v[22:25]
	v_mfma_f32_16x16x32_bf16 v[18:21], v[156:159], v[180:183], v[18:21]
	v_mfma_f32_16x16x32_bf16 v[6:9], v[148:151], v[188:191], v[6:9]
	v_mfma_f32_16x16x32_bf16 v[2:5], v[156:159], v[188:191], v[2:5]
	v_mfma_f32_16x16x32_bf16 v[54:57], v[152:155], v[168:171], v[54:57]
	v_mfma_f32_16x16x32_bf16 v[50:53], v[160:163], v[168:171], v[50:53]
	v_mfma_f32_16x16x32_bf16 v[38:41], v[152:155], v[176:179], v[38:41]
	v_mfma_f32_16x16x32_bf16 v[34:37], v[160:163], v[176:179], v[34:37]
	v_mfma_f32_16x16x32_bf16 v[22:25], v[152:155], v[184:187], v[22:25]
	v_mfma_f32_16x16x32_bf16 v[18:21], v[160:163], v[184:187], v[18:21]
	v_mfma_f32_16x16x32_bf16 v[6:9], v[152:155], v[192:195], v[6:9]
	v_mfma_f32_16x16x32_bf16 v[2:5], v[160:163], v[192:195], v[2:5]
	s_barrier
; #define PG8_STAGE(bufoff, gbase, voff) do { _Pragma("unroll") for (int _i = 0; _i < 2; ++_i) \
;         __builtin_amdgcn_global_load_lds((const gunsigned*)((const gchar*)(gbase) + (voff)[_i]), (LAS unsigned*)(lds + (bufoff) + ldsw + _i * 8192), 16, 0, 0); } while (0)
; #define PG8_LDA(dst, b, h) do { _Pragma("unroll") for (int m = 0; m < 4; ++m) _Pragma("unroll") for (int k = 0; k < 2; ++k) dst[m][k] = *(const LAS bf16x8*)(lds + PG8_SA(b, h) + aoff + m * 2048 + k * 1024); } while (0)
; #define PG8_LDB(dst, b, h) do { _Pragma("unroll") for (int n = 0; n < 2; ++n) _Pragma("unroll") for (int k = 0; k < 2; ++k) dst[n][k] = *(const LAS bf16x8*)(lds + PG8_SB(b, h) + boff + n * 2048 + k * 1024); } while (0)
; #define PG8_MMA(ai, bj, At, Bt) do { __builtin_amdgcn_s_setprio(1); _Pragma("unroll") for (int m = 0; m < 4; ++m) _Pragma("unroll") for (int n = 0; n < 2; ++n) _Pragma("unroll") for (int k = 0; k < 2; ++k) \
;         acc[ai][bj][m][n] = __builtin_amdgcn_mfma_f32_16x16x32_bf16(Bt[n][k], At[m][k], acc[ai][bj][m][n], 0, 0, 0); __builtin_amdgcn_s_setprio(0); } while (0)
; #define PG8_WAIT_V(n) asm volatile("s_waitcnt vmcnt(" #n ")" ::: "memory")
; #define PG8_WAIT_L(n) asm volatile("s_waitcnt lgkmcnt(" #n ")" ::: "memory")
; #define PG8_BAR __builtin_amdgcn_s_barrier()
; #define PG8_SCHED __builtin_amdgcn_sched_barrier(0)
; template <class Epi, class Sched>
; __device__ __forceinline__ void gemm_phase(LAS unsigned char* lds, const int tid, const Gemm g, const Sched& S, const Epi& E) {
;     ...
;             PG8_LDB(B0, 1, 0); PG8_LDB(B1, 1, 1); PG8_SCHED; PG8_LDA(At, 1, 0); PG8_STAGE(PG8_SA(0, 1), a2 + hstep, voffA);
;             PG8_WAIT_V(8); PG8_WAIT_L(0); PG8_BAR; PG8_MMA(0, 0, At, B0); PG8_MMA(0, 1, At, B1); PG8_BAR; PG8_SCHED;
;             PG8_LDA(At, 1, 1); PG8_STAGE(PG8_SB(1, 0), b3, voffB); PG8_STAGE(PG8_SB(1, 1), b3 + hstep, voffB); PG8_STAGE(PG8_SA(1, 0), a3, voffA);
;             PG8_WAIT_V(8); PG8_WAIT_L(0); PG8_BAR; PG8_MMA(1, 0, At, B0); PG8_MMA(1, 1, At, B1); PG8_BAR; PG8_SCHED;
;         }
;         if (wr == 0) PG8_BAR;
	s_setprio 0
	s_add_i32 s29, 0, 0x18000
	v_add_u32_e32 v126, s29, v242
	s_add_i32 s30, 0, 0x1c000
	ds_read_b128 v[132:135], v126
	ds_read_b128 v[136:139], v126 offset:1024
	ds_read_b128 v[140:143], v126 offset:2048
	ds_read_b128 v[144:147], v126 offset:3072
	v_add_u32_e32 v126, s30, v242
	ds_read_b128 v[148:151], v126
	ds_read_b128 v[152:155], v126 offset:1024
	ds_read_b128 v[156:159], v126 offset:2048
	ds_read_b128 v[160:163], v126 offset:3072
	s_add_u32 s52, s72, 0x20000
	s_addc_u32 s53, s73, 0
	s_mov_b32 m0, s45
	ds_read_b128 v[164:167], v244 offset:32768
	ds_read_b128 v[168:171], v244 offset:33792
	ds_read_b128 v[172:175], v244 offset:34816
	ds_read_b128 v[176:179], v244 offset:35840
	ds_read_b128 v[180:183], v244 offset:36864
	ds_read_b128 v[184:187], v244 offset:37888
	ds_read_b128 v[188:191], v244 offset:38912
	ds_read_b128 v[192:195], v244 offset:39936
	global_load_lds_dwordx4 v204, s[52:53]
	s_mov_b32 m0, s46
	s_nop 0
	global_load_lds_dwordx4 v206, s[52:53]
	s_waitcnt vmcnt(8)
	s_waitcnt lgkmcnt(0)
	s_setprio 1
	s_barrier
	v_mfma_f32_16x16x32_bf16 v[126:129], v[132:135], v[164:167], v[128:131]
	v_mfma_f32_16x16x32_bf16 v[122:125], v[140:143], v[164:167], v[122:125]
	v_mfma_f32_16x16x32_bf16 v[110:113], v[132:135], v[172:175], v[110:113]
	v_mfma_f32_16x16x32_bf16 v[106:109], v[140:143], v[172:175], v[106:109]
	v_mfma_f32_16x16x32_bf16 v[94:97], v[132:135], v[180:183], v[94:97]
	v_mfma_f32_16x16x32_bf16 v[90:93], v[140:143], v[180:183], v[90:93]
	v_mfma_f32_16x16x32_bf16 v[78:81], v[132:135], v[188:191], v[78:81]
	v_mfma_f32_16x16x32_bf16 v[74:77], v[140:143], v[188:191], v[74:77]
	v_mfma_f32_16x16x32_bf16 v[128:131], v[136:139], v[168:171], v[126:129]
	v_mfma_f32_16x16x32_bf16 v[124:127], v[144:147], v[168:171], v[122:125]
	v_mfma_f32_16x16x32_bf16 v[110:113], v[136:139], v[176:179], v[110:113]
	v_mfma_f32_16x16x32_bf16 v[106:109], v[144:147], v[176:179], v[106:109]
	v_mfma_f32_16x16x32_bf16 v[94:97], v[136:139], v[184:187], v[94:97]
	v_mfma_f32_16x16x32_bf16 v[90:93], v[144:147], v[184:187], v[90:93]
	v_mfma_f32_16x16x32_bf16 v[78:81], v[136:139], v[192:195], v[78:81]
	v_mfma_f32_16x16x32_bf16 v[74:77], v[144:147], v[192:195], v[74:77]
	s_setprio 0
	s_setprio 1
	v_mfma_f32_16x16x32_bf16 v[118:121], v[148:151], v[164:167], v[118:121]
	v_mfma_f32_16x16x32_bf16 v[114:117], v[156:159], v[164:167], v[114:117]
	v_mfma_f32_16x16x32_bf16 v[102:105], v[148:151], v[172:175], v[102:105]
	v_mfma_f32_16x16x32_bf16 v[98:101], v[156:159], v[172:175], v[98:101]
	v_mfma_f32_16x16x32_bf16 v[86:89], v[148:151], v[180:183], v[86:89]
	v_mfma_f32_16x16x32_bf16 v[82:85], v[156:159], v[180:183], v[82:85]
	v_mfma_f32_16x16x32_bf16 v[70:73], v[148:151], v[188:191], v[70:73]
	v_mfma_f32_16x16x32_bf16 v[66:69], v[156:159], v[188:191], v[66:69]
	v_mfma_f32_16x16x32_bf16 v[118:121], v[152:155], v[168:171], v[118:121]
	v_mfma_f32_16x16x32_bf16 v[114:117], v[160:163], v[168:171], v[114:117]
	v_mfma_f32_16x16x32_bf16 v[102:105], v[152:155], v[176:179], v[102:105]
	v_mfma_f32_16x16x32_bf16 v[98:101], v[160:163], v[176:179], v[98:101]
	v_mfma_f32_16x16x32_bf16 v[86:89], v[152:155], v[184:187], v[86:89]
	v_mfma_f32_16x16x32_bf16 v[82:85], v[160:163], v[184:187], v[82:85]
	v_mfma_f32_16x16x32_bf16 v[70:73], v[152:155], v[192:195], v[70:73]
	v_mfma_f32_16x16x32_bf16 v[66:69], v[160:163], v[192:195], v[66:69]
	s_barrier
	s_setprio 0
	s_add_i32 s29, s29, s42
	s_mov_b32 m0, s29
	ds_read_b128 v[164:167], v244 offset:49152
	ds_read_b128 v[168:171], v244 offset:50176
	ds_read_b128 v[172:175], v244 offset:51200
	ds_read_b128 v[176:179], v244 offset:52224
	ds_read_b128 v[180:183], v244 offset:53248
	ds_read_b128 v[184:187], v244 offset:54272
	ds_read_b128 v[188:191], v244 offset:55296
	ds_read_b128 v[192:195], v244 offset:56320
	global_load_lds_dwordx4 v201, s[20:21]
	s_add_i32 m0, s29, 0x2000
	s_add_i32 s29, s30, s42
	global_load_lds_dwordx4 v215, s[20:21]
	s_add_u32 s20, s20, 0x20080
	s_addc_u32 s21, s21, 0
	s_mov_b32 m0, s29
	s_nop 0
	global_load_lds_dwordx4 v0, s[20:21]
	s_add_i32 m0, s29, 0x2000
	s_nop 0
	global_load_lds_dwordx4 v208, s[20:21]
	s_mov_b32 m0, s47
	s_nop 0
	global_load_lds_dwordx4 v217, s[72:73]
	s_mov_b32 m0, s48
	s_nop 0
	global_load_lds_dwordx4 v219, s[72:73]
	s_waitcnt vmcnt(8)
	s_waitcnt lgkmcnt(0)
	s_setprio 1
	s_barrier
	v_mfma_f32_16x16x32_bf16 v[62:65], v[132:135], v[164:167], v[62:65]
	v_mfma_f32_16x16x32_bf16 v[58:61], v[140:143], v[164:167], v[58:61]
	v_mfma_f32_16x16x32_bf16 v[46:49], v[132:135], v[172:175], v[46:49]
	v_mfma_f32_16x16x32_bf16 v[42:45], v[140:143], v[172:175], v[42:45]
	v_mfma_f32_16x16x32_bf16 v[30:33], v[132:135], v[180:183], v[30:33]
	v_mfma_f32_16x16x32_bf16 v[26:29], v[140:143], v[180:183], v[26:29]
	v_mfma_f32_16x16x32_bf16 v[14:17], v[132:135], v[188:191], v[14:17]
	v_mfma_f32_16x16x32_bf16 v[10:13], v[140:143], v[188:191], v[10:13]
	v_mfma_f32_16x16x32_bf16 v[62:65], v[136:139], v[168:171], v[62:65]
	v_mfma_f32_16x16x32_bf16 v[58:61], v[144:147], v[168:171], v[58:61]
	v_mfma_f32_16x16x32_bf16 v[46:49], v[136:139], v[176:179], v[46:49]
	v_mfma_f32_16x16x32_bf16 v[42:45], v[144:147], v[176:179], v[42:45]
	v_mfma_f32_16x16x32_bf16 v[30:33], v[136:139], v[184:187], v[30:33]
	v_mfma_f32_16x16x32_bf16 v[26:29], v[144:147], v[184:187], v[26:29]
	v_mfma_f32_16x16x32_bf16 v[14:17], v[136:139], v[192:195], v[14:17]
	v_mfma_f32_16x16x32_bf16 v[10:13], v[144:147], v[192:195], v[10:13]
	s_setprio 0
	s_setprio 1
	v_mfma_f32_16x16x32_bf16 v[54:57], v[148:151], v[164:167], v[54:57]
	v_mfma_f32_16x16x32_bf16 v[50:53], v[156:159], v[164:167], v[50:53]
	v_mfma_f32_16x16x32_bf16 v[38:41], v[148:151], v[172:175], v[38:41]
	v_mfma_f32_16x16x32_bf16 v[34:37], v[156:159], v[172:175], v[34:37]
	v_mfma_f32_16x16x32_bf16 v[22:25], v[148:151], v[180:183], v[22:25]
	v_mfma_f32_16x16x32_bf16 v[18:21], v[156:159], v[180:183], v[18:21]
	v_mfma_f32_16x16x32_bf16 v[6:9], v[148:151], v[188:191], v[6:9]
	v_mfma_f32_16x16x32_bf16 v[2:5], v[156:159], v[188:191], v[2:5]
	v_mfma_f32_16x16x32_bf16 v[54:57], v[152:155], v[168:171], v[54:57]
	v_mfma_f32_16x16x32_bf16 v[50:53], v[160:163], v[168:171], v[50:53]
	v_mfma_f32_16x16x32_bf16 v[38:41], v[152:155], v[176:179], v[38:41]
	v_mfma_f32_16x16x32_bf16 v[34:37], v[160:163], v[176:179], v[34:37]
	v_mfma_f32_16x16x32_bf16 v[22:25], v[152:155], v[184:187], v[22:25]
	v_mfma_f32_16x16x32_bf16 v[18:21], v[160:163], v[184:187], v[18:21]
	v_mfma_f32_16x16x32_bf16 v[6:9], v[152:155], v[192:195], v[6:9]
	v_mfma_f32_16x16x32_bf16 v[2:5], v[160:163], v[192:195], v[2:5]
	s_barrier
	s_setprio 0
	s_add_i32 s51, s51, 2
	s_add_u32 s24, s24, 0x100
	s_addc_u32 s31, s31, 0
	s_add_u32 s16, s16, 0x100
	s_addc_u32 s17, s17, 0
	s_cmp_gt_u32 s51, 5
	s_cbranch_scc0 .LBB0_444
	s_and_b64 vcc, exec, s[10:11]
	s_cbranch_vccz .LBB0_447
	s_barrier

; #define PG8_STAGE(bufoff, gbase, voff) do { _Pragma("unroll") for (int _i = 0; _i < 2; ++_i) \
;         __builtin_amdgcn_global_load_lds((const gunsigned*)((const gchar*)(gbase) + (voff)[_i]), (LAS unsigned*)(lds + (bufoff) + ldsw + _i * 8192), 16, 0, 0); } while (0)
; #define PG8_LDA(dst, b, h) do { _Pragma("unroll") for (int m = 0; m < 4; ++m) _Pragma("unroll") for (int k = 0; k < 2; ++k) dst[m][k] = *(const LAS bf16x8*)(lds + PG8_SA(b, h) + aoff + m * 2048 + k * 1024); } while (0)
; #define PG8_LDB(dst, b, h) do { _Pragma("unroll") for (int n = 0; n < 2; ++n) _Pragma("unroll") for (int k = 0; k < 2; ++k) dst[n][k] = *(const LAS bf16x8*)(lds + PG8_SB(b, h) + boff + n * 2048 + k * 1024); } while (0)
; #define PG8_MMA(ai, bj, At, Bt) do { __builtin_amdgcn_s_setprio(1); _Pragma("unroll") for (int m = 0; m < 4; ++m) _Pragma("unroll") for (int n = 0; n < 2; ++n) _Pragma("unroll") for (int k = 0; k < 2; ++k) \
;         acc[ai][bj][m][n] = __builtin_amdgcn_mfma_f32_16x16x32_bf16(Bt[n][k], At[m][k], acc[ai][bj][m][n], 0, 0, 0); __builtin_amdgcn_s_setprio(0); } while (0)
; #define PG8_WAIT_V(n) asm volatile("s_waitcnt vmcnt(" #n ")" ::: "memory")
; #define PG8_WAIT_L(n) asm volatile("s_waitcnt lgkmcnt(" #n ")" ::: "memory")
; #define PG8_BAR __builtin_amdgcn_s_barrier()
; #define PG8_SCHED __builtin_amdgcn_sched_barrier(0)
; template <class Epi, class Sched>
; __device__ __forceinline__ void gemm_phase(LAS unsigned char* lds, const int tid, const Gemm g, const Sched& S, const Epi& E) {
;     ...
;         for (int t = 0; t < nt; t += 2) {
;             const bool last = (t == nt - 2);
;             const gchar* a1 = cA + (size_t)(t + 1) * kstep;
;             const gchar* a2 = last ? nA : cA + (size_t)(t + 2) * kstep; const gchar* b2 = last ? nB : cB + (size_t)(t + 2) * kstep;
;             const gchar* a3 = a2 + kstep; const gchar* b3 = b2 + kstep;
;             PG8_LDB(B0, 0, 0); PG8_LDB(B1, 0, 1); PG8_SCHED; PG8_LDA(At, 0, 0); PG8_STAGE(PG8_SA(1, 1), a1 + hstep, voffA);
;             PG8_WAIT_V(8); PG8_WAIT_L(0); PG8_BAR; PG8_MMA(0, 0, At, B0); PG8_MMA(0, 1, At, B1); PG8_BAR; PG8_SCHED;
;             PG8_LDA(At, 0, 1); PG8_STAGE(PG8_SB(0, 0), b2, voffB); PG8_STAGE(PG8_SB(0, 1), b2 + hstep, voffB); PG8_STAGE(PG8_SA(0, 0), a2, voffA);
;             PG8_WAIT_V(8); PG8_WAIT_L(0); PG8_BAR; PG8_MMA(1, 0, At, B0); PG8_MMA(1, 1, At, B1); PG8_BAR; PG8_SCHED;
.LBB0_559:
	s_add_u32 s20, s60, 0xfffc0080
	s_addc_u32 s21, s61, -1
	s_add_i32 s29, 0, 0x10000
	s_cmp_eq_u32 s46, 12
	s_cselect_b32 s63, s9, s21
	s_cselect_b32 s62, s42, s20
	s_cselect_b32 s21, s7, s45
	s_cselect_b32 s20, s43, s44
	s_add_i32 s30, 0, 0x14000
	v_add_u32_e32 v152, s29, v165
	v_add_u32_e32 v160, s30, v165
	ds_read_b128 v[130:133], v152
	ds_read_b128 v[144:147], v152 offset:1024
	ds_read_b128 v[148:151], v152 offset:2048
	ds_read_b128 v[152:155], v152 offset:3072
	ds_read_b128 v[156:159], v160
	ds_read_b128 v[170:173], v160 offset:1024
	ds_read_b128 v[174:177], v160 offset:2048
	ds_read_b128 v[178:181], v160 offset:3072
	s_add_i32 m0, s34, 0xc000
	ds_read_b128 v[182:185], v169
	ds_read_b128 v[186:189], v169 offset:1024
	ds_read_b128 v[190:193], v169 offset:2048
	ds_read_b128 v[204:207], v169 offset:3072
	ds_read_b128 v[210:213], v169 offset:4096
	ds_read_b128 v[214:217], v169 offset:5120
	ds_read_b128 v[218:221], v169 offset:6144
	ds_read_b128 v[222:225], v169 offset:7168
	global_load_lds_dwordx4 v142, s[60:61]
	s_add_i32 m0, s34, 0xe000
	s_nop 0
	global_load_lds_dwordx4 v140, s[60:61]
	s_waitcnt vmcnt(8)
	s_waitcnt lgkmcnt(0)
	s_setprio 1
	s_barrier
	v_mfma_f32_16x16x32_bf16 v[126:129], v[130:133], v[182:185], v[126:129]
	v_mfma_f32_16x16x32_bf16 v[122:125], v[148:151], v[182:185], v[122:125]
	v_mfma_f32_16x16x32_bf16 v[118:121], v[130:133], v[190:193], v[118:121]
	v_mfma_f32_16x16x32_bf16 v[110:113], v[148:151], v[190:193], v[110:113]
	v_mfma_f32_16x16x32_bf16 v[102:105], v[130:133], v[210:213], v[102:105]
	v_mfma_f32_16x16x32_bf16 v[94:97], v[148:151], v[210:213], v[94:97]
	v_mfma_f32_16x16x32_bf16 v[86:89], v[130:133], v[218:221], v[86:89]
	v_mfma_f32_16x16x32_bf16 v[78:81], v[148:151], v[218:221], v[78:81]
	v_mfma_f32_16x16x32_bf16 v[126:129], v[144:147], v[186:189], v[126:129]
	v_mfma_f32_16x16x32_bf16 v[122:125], v[152:155], v[186:189], v[122:125]
	v_mfma_f32_16x16x32_bf16 v[118:121], v[144:147], v[204:207], v[118:121]
	v_mfma_f32_16x16x32_bf16 v[110:113], v[152:155], v[204:207], v[110:113]
	v_mfma_f32_16x16x32_bf16 v[102:105], v[144:147], v[214:217], v[102:105]
	v_mfma_f32_16x16x32_bf16 v[94:97], v[152:155], v[214:217], v[94:97]
	v_mfma_f32_16x16x32_bf16 v[86:89], v[144:147], v[222:225], v[86:89]
	v_mfma_f32_16x16x32_bf16 v[78:81], v[152:155], v[222:225], v[78:81]
	s_setprio 0
	s_setprio 1
	v_mfma_f32_16x16x32_bf16 v[114:117], v[156:159], v[182:185], v[114:117]
	v_mfma_f32_16x16x32_bf16 v[106:109], v[174:177], v[182:185], v[106:109]
	v_mfma_f32_16x16x32_bf16 v[98:101], v[156:159], v[190:193], v[98:101]
	v_mfma_f32_16x16x32_bf16 v[90:93], v[174:177], v[190:193], v[90:93]
	v_mfma_f32_16x16x32_bf16 v[82:85], v[156:159], v[210:213], v[82:85]
	v_mfma_f32_16x16x32_bf16 v[74:77], v[174:177], v[210:213], v[74:77]
	v_mfma_f32_16x16x32_bf16 v[70:73], v[156:159], v[218:221], v[70:73]
	v_mfma_f32_16x16x32_bf16 v[66:69], v[174:177], v[218:221], v[66:69]
	v_mfma_f32_16x16x32_bf16 v[114:117], v[170:173], v[186:189], v[114:117]
	v_mfma_f32_16x16x32_bf16 v[106:109], v[178:181], v[186:189], v[106:109]
	v_mfma_f32_16x16x32_bf16 v[98:101], v[170:173], v[204:207], v[98:101]
	v_mfma_f32_16x16x32_bf16 v[90:93], v[178:181], v[204:207], v[90:93]
	v_mfma_f32_16x16x32_bf16 v[82:85], v[170:173], v[214:217], v[82:85]
	v_mfma_f32_16x16x32_bf16 v[74:77], v[178:181], v[214:217], v[74:77]
	v_mfma_f32_16x16x32_bf16 v[70:73], v[170:173], v[222:225], v[70:73]
	v_mfma_f32_16x16x32_bf16 v[66:69], v[178:181], v[222:225], v[66:69]
	s_barrier
	s_setprio 0
	s_add_i32 s29, s29, s12
	s_mov_b32 m0, s29
	ds_read_b128 v[182:185], v169 offset:16384
	ds_read_b128 v[186:189], v169 offset:17408
	ds_read_b128 v[190:193], v169 offset:18432
	ds_read_b128 v[204:207], v169 offset:19456
	ds_read_b128 v[210:213], v169 offset:20480
	ds_read_b128 v[214:217], v169 offset:21504
	ds_read_b128 v[218:221], v169 offset:22528
	ds_read_b128 v[222:225], v169 offset:23552
	global_load_lds_dwordx4 v0, s[20:21]
	s_add_i32 m0, s29, 0x2000
	s_add_u32 s48, s20, 0x40000
	s_addc_u32 s49, s21, 0
	s_add_i32 s29, s30, s12
	global_load_lds_dwordx4 v134, s[20:21]
	s_mov_b32 m0, s29
	s_nop 0
	global_load_lds_dwordx4 v0, s[48:49]
	s_add_i32 m0, s29, 0x2000
	s_nop 0
	global_load_lds_dwordx4 v134, s[48:49]
	s_mov_b32 m0, s34
	s_nop 0
	global_load_lds_dwordx4 v138, s[62:63]
	s_mov_b32 m0, s35
	s_nop 0
	global_load_lds_dwordx4 v136, s[62:63]
	s_waitcnt vmcnt(8)
	s_waitcnt lgkmcnt(0)
	s_setprio 1
	s_barrier
	v_mfma_f32_16x16x32_bf16 v[62:65], v[130:133], v[182:185], v[62:65]
	v_mfma_f32_16x16x32_bf16 v[58:61], v[148:151], v[182:185], v[58:61]
	v_mfma_f32_16x16x32_bf16 v[54:57], v[130:133], v[190:193], v[54:57]
	v_mfma_f32_16x16x32_bf16 v[46:49], v[148:151], v[190:193], v[46:49]
	v_mfma_f32_16x16x32_bf16 v[38:41], v[130:133], v[210:213], v[38:41]
	v_mfma_f32_16x16x32_bf16 v[30:33], v[148:151], v[210:213], v[30:33]
	v_mfma_f32_16x16x32_bf16 v[22:25], v[130:133], v[218:221], v[22:25]
	v_mfma_f32_16x16x32_bf16 v[14:17], v[148:151], v[218:221], v[14:17]
	v_mfma_f32_16x16x32_bf16 v[62:65], v[144:147], v[186:189], v[62:65]
	v_mfma_f32_16x16x32_bf16 v[58:61], v[152:155], v[186:189], v[58:61]
	v_mfma_f32_16x16x32_bf16 v[54:57], v[144:147], v[204:207], v[54:57]
	v_mfma_f32_16x16x32_bf16 v[46:49], v[152:155], v[204:207], v[46:49]
	v_mfma_f32_16x16x32_bf16 v[38:41], v[144:147], v[214:217], v[38:41]
	v_mfma_f32_16x16x32_bf16 v[30:33], v[152:155], v[214:217], v[30:33]
	v_mfma_f32_16x16x32_bf16 v[22:25], v[144:147], v[222:225], v[22:25]
	v_mfma_f32_16x16x32_bf16 v[14:17], v[152:155], v[222:225], v[14:17]
	s_setprio 0
	s_setprio 1
	v_mfma_f32_16x16x32_bf16 v[50:53], v[156:159], v[182:185], v[50:53]
	v_mfma_f32_16x16x32_bf16 v[42:45], v[174:177], v[182:185], v[42:45]
	v_mfma_f32_16x16x32_bf16 v[34:37], v[156:159], v[190:193], v[34:37]
	v_mfma_f32_16x16x32_bf16 v[26:29], v[174:177], v[190:193], v[26:29]
	v_mfma_f32_16x16x32_bf16 v[18:21], v[156:159], v[210:213], v[18:21]
	v_mfma_f32_16x16x32_bf16 v[10:13], v[174:177], v[210:213], v[10:13]
	v_mfma_f32_16x16x32_bf16 v[6:9], v[156:159], v[218:221], v[6:9]
	v_mfma_f32_16x16x32_bf16 v[2:5], v[174:177], v[218:221], v[2:5]
	v_mfma_f32_16x16x32_bf16 v[50:53], v[170:173], v[186:189], v[50:53]
	v_mfma_f32_16x16x32_bf16 v[42:45], v[178:181], v[186:189], v[42:45]
	v_mfma_f32_16x16x32_bf16 v[34:37], v[170:173], v[204:207], v[34:37]
	v_mfma_f32_16x16x32_bf16 v[26:29], v[178:181], v[204:207], v[26:29]
	v_mfma_f32_16x16x32_bf16 v[18:21], v[170:173], v[214:217], v[18:21]
	v_mfma_f32_16x16x32_bf16 v[10:13], v[178:181], v[214:217], v[10:13]
	v_mfma_f32_16x16x32_bf16 v[6:9], v[170:173], v[222:225], v[6:9]
	v_mfma_f32_16x16x32_bf16 v[2:5], v[178:181], v[222:225], v[2:5]
	s_barrier
; #define PG8_STAGE(bufoff, gbase, voff) do { _Pragma("unroll") for (int _i = 0; _i < 2; ++_i) \
;         __builtin_amdgcn_global_load_lds((const gunsigned*)((const gchar*)(gbase) + (voff)[_i]), (LAS unsigned*)(lds + (bufoff) + ldsw + _i * 8192), 16, 0, 0); } while (0)
; #define PG8_LDA(dst, b, h) do { _Pragma("unroll") for (int m = 0; m < 4; ++m) _Pragma("unroll") for (int k = 0; k < 2; ++k) dst[m][k] = *(const LAS bf16x8*)(lds + PG8_SA(b, h) + aoff + m * 2048 + k * 1024); } while (0)
; #define PG8_LDB(dst, b, h) do { _Pragma("unroll") for (int n = 0; n < 2; ++n) _Pragma("unroll") for (int k = 0; k < 2; ++k) dst[n][k] = *(const LAS bf16x8*)(lds + PG8_SB(b, h) + boff + n * 2048 + k * 1024); } while (0)
; #define PG8_MMA(ai, bj, At, Bt) do { __builtin_amdgcn_s_setprio(1); _Pragma("unroll") for (int m = 0; m < 4; ++m) _Pragma("unroll") for (int n = 0; n < 2; ++n) _Pragma("unroll") for (int k = 0; k < 2; ++k) \
;         acc[ai][bj][m][n] = __builtin_amdgcn_mfma_f32_16x16x32_bf16(Bt[n][k], At[m][k], acc[ai][bj][m][n], 0, 0, 0); __builtin_amdgcn_s_setprio(0); } while (0)
; #define PG8_WAIT_V(n) asm volatile("s_waitcnt vmcnt(" #n ")" ::: "memory")
; #define PG8_WAIT_L(n) asm volatile("s_waitcnt lgkmcnt(" #n ")" ::: "memory")
; #define PG8_BAR __builtin_amdgcn_s_barrier()
; #define PG8_SCHED __builtin_amdgcn_sched_barrier(0)
; template <class Epi, class Sched>
; __device__ __forceinline__ void gemm_phase(LAS unsigned char* lds, const int tid, const Gemm g, const Sched& S, const Epi& E) {
;     ...
;             PG8_LDB(B0, 1, 0); PG8_LDB(B1, 1, 1); PG8_SCHED; PG8_LDA(At, 1, 0); PG8_STAGE(PG8_SA(0, 1), a2 + hstep, voffA);
;             PG8_WAIT_V(8); PG8_WAIT_L(0); PG8_BAR; PG8_MMA(0, 0, At, B0); PG8_MMA(0, 1, At, B1); PG8_BAR; PG8_SCHED;
;             PG8_LDA(At, 1, 1); PG8_STAGE(PG8_SB(1, 0), b3, voffB); PG8_STAGE(PG8_SB(1, 1), b3 + hstep, voffB); PG8_STAGE(PG8_SA(1, 0), a3, voffA);
;             PG8_WAIT_V(8); PG8_WAIT_L(0); PG8_BAR; PG8_MMA(1, 0, At, B0); PG8_MMA(1, 1, At, B1); PG8_BAR; PG8_SCHED;
;         }
;         if (wr == 0) PG8_BAR;
	s_setprio 0
	s_add_i32 s29, 0, 0x18000
	s_add_i32 s30, 0, 0x1c000
	v_add_u32_e32 v152, s29, v165
	v_add_u32_e32 v162, s30, v165
	ds_read_b128 v[130:133], v152
	ds_read_b128 v[144:147], v152 offset:1024
	ds_read_b128 v[148:151], v152 offset:2048
	ds_read_b128 v[152:155], v152 offset:3072
	ds_read_b128 v[156:159], v162
	ds_read_b128 v[170:173], v162 offset:1024
	ds_read_b128 v[174:177], v162 offset:2048
	ds_read_b128 v[178:181], v162 offset:3072
	s_add_u32 s48, s62, 0x40000
	s_addc_u32 s49, s63, 0
	s_mov_b32 m0, s36
	ds_read_b128 v[182:185], v169 offset:32768
	ds_read_b128 v[186:189], v169 offset:33792
	ds_read_b128 v[190:193], v169 offset:34816
	ds_read_b128 v[204:207], v169 offset:35840
	ds_read_b128 v[210:213], v169 offset:36864
	ds_read_b128 v[214:217], v169 offset:37888
	ds_read_b128 v[218:221], v169 offset:38912
	ds_read_b128 v[222:225], v169 offset:39936
	global_load_lds_dwordx4 v138, s[48:49]
	s_mov_b32 m0, s37
	s_nop 0
	global_load_lds_dwordx4 v136, s[48:49]
	s_waitcnt vmcnt(8)
	s_waitcnt lgkmcnt(0)
	s_setprio 1
	s_barrier
	v_mfma_f32_16x16x32_bf16 v[126:129], v[130:133], v[182:185], v[126:129]
	v_mfma_f32_16x16x32_bf16 v[122:125], v[148:151], v[182:185], v[122:125]
	v_mfma_f32_16x16x32_bf16 v[118:121], v[130:133], v[190:193], v[118:121]
	v_mfma_f32_16x16x32_bf16 v[110:113], v[148:151], v[190:193], v[110:113]
	v_mfma_f32_16x16x32_bf16 v[102:105], v[130:133], v[210:213], v[102:105]
	v_mfma_f32_16x16x32_bf16 v[94:97], v[148:151], v[210:213], v[94:97]
	v_mfma_f32_16x16x32_bf16 v[86:89], v[130:133], v[218:221], v[86:89]
	v_mfma_f32_16x16x32_bf16 v[78:81], v[148:151], v[218:221], v[78:81]
	v_mfma_f32_16x16x32_bf16 v[126:129], v[144:147], v[186:189], v[126:129]
	v_mfma_f32_16x16x32_bf16 v[122:125], v[152:155], v[186:189], v[122:125]
	v_mfma_f32_16x16x32_bf16 v[118:121], v[144:147], v[204:207], v[118:121]
	v_mfma_f32_16x16x32_bf16 v[110:113], v[152:155], v[204:207], v[110:113]
	v_mfma_f32_16x16x32_bf16 v[102:105], v[144:147], v[214:217], v[102:105]
	v_mfma_f32_16x16x32_bf16 v[94:97], v[152:155], v[214:217], v[94:97]
	v_mfma_f32_16x16x32_bf16 v[86:89], v[144:147], v[222:225], v[86:89]
	v_mfma_f32_16x16x32_bf16 v[78:81], v[152:155], v[222:225], v[78:81]
	s_setprio 0
	s_setprio 1
	v_mfma_f32_16x16x32_bf16 v[114:117], v[156:159], v[182:185], v[114:117]
	v_mfma_f32_16x16x32_bf16 v[106:109], v[174:177], v[182:185], v[106:109]
	v_mfma_f32_16x16x32_bf16 v[98:101], v[156:159], v[190:193], v[98:101]
	v_mfma_f32_16x16x32_bf16 v[90:93], v[174:177], v[190:193], v[90:93]
	v_mfma_f32_16x16x32_bf16 v[82:85], v[156:159], v[210:213], v[82:85]
	v_mfma_f32_16x16x32_bf16 v[74:77], v[174:177], v[210:213], v[74:77]
	v_mfma_f32_16x16x32_bf16 v[70:73], v[156:159], v[218:221], v[70:73]
	v_mfma_f32_16x16x32_bf16 v[66:69], v[174:177], v[218:221], v[66:69]
	v_mfma_f32_16x16x32_bf16 v[114:117], v[170:173], v[186:189], v[114:117]
	v_mfma_f32_16x16x32_bf16 v[106:109], v[178:181], v[186:189], v[106:109]
	v_mfma_f32_16x16x32_bf16 v[98:101], v[170:173], v[204:207], v[98:101]
	v_mfma_f32_16x16x32_bf16 v[90:93], v[178:181], v[204:207], v[90:93]
	v_mfma_f32_16x16x32_bf16 v[82:85], v[170:173], v[214:217], v[82:85]
	v_mfma_f32_16x16x32_bf16 v[74:77], v[178:181], v[214:217], v[74:77]
	v_mfma_f32_16x16x32_bf16 v[70:73], v[170:173], v[222:225], v[70:73]
	v_mfma_f32_16x16x32_bf16 v[66:69], v[178:181], v[222:225], v[66:69]
	s_barrier
	s_setprio 0
	s_add_i32 s29, s29, s12
	s_mov_b32 m0, s29
	ds_read_b128 v[182:185], v169 offset:49152
	ds_read_b128 v[186:189], v169 offset:50176
	ds_read_b128 v[190:193], v169 offset:51200
	ds_read_b128 v[204:207], v169 offset:52224
	ds_read_b128 v[210:213], v169 offset:53248
	ds_read_b128 v[214:217], v169 offset:54272
	ds_read_b128 v[218:221], v169 offset:55296
	ds_read_b128 v[222:225], v169 offset:56320
	global_load_lds_dwordx4 v161, s[20:21]
	s_add_i32 m0, s29, 0x2000
	s_add_i32 s29, s30, s12
	global_load_lds_dwordx4 v195, s[20:21]
	s_add_u32 s20, s20, 0x40080
	s_addc_u32 s21, s21, 0
	s_mov_b32 m0, s29
	s_nop 0
	global_load_lds_dwordx4 v0, s[20:21]
	s_add_i32 m0, s29, 0x2000
	s_nop 0
	global_load_lds_dwordx4 v134, s[20:21]
	s_mov_b32 m0, s38
	s_nop 0
	global_load_lds_dwordx4 v201, s[62:63]
	s_mov_b32 m0, s39
	s_nop 0
	global_load_lds_dwordx4 v227, s[62:63]
	s_waitcnt vmcnt(8)
	s_waitcnt lgkmcnt(0)
	s_setprio 1
	s_barrier
	v_mfma_f32_16x16x32_bf16 v[62:65], v[130:133], v[182:185], v[62:65]
	v_mfma_f32_16x16x32_bf16 v[58:61], v[148:151], v[182:185], v[58:61]
	v_mfma_f32_16x16x32_bf16 v[54:57], v[130:133], v[190:193], v[54:57]
	v_mfma_f32_16x16x32_bf16 v[46:49], v[148:151], v[190:193], v[46:49]
	v_mfma_f32_16x16x32_bf16 v[38:41], v[130:133], v[210:213], v[38:41]
	v_mfma_f32_16x16x32_bf16 v[30:33], v[148:151], v[210:213], v[30:33]
	v_mfma_f32_16x16x32_bf16 v[22:25], v[130:133], v[218:221], v[22:25]
	v_mfma_f32_16x16x32_bf16 v[14:17], v[148:151], v[218:221], v[14:17]
	v_mfma_f32_16x16x32_bf16 v[62:65], v[144:147], v[186:189], v[62:65]
	v_mfma_f32_16x16x32_bf16 v[58:61], v[152:155], v[186:189], v[58:61]
	v_mfma_f32_16x16x32_bf16 v[54:57], v[144:147], v[204:207], v[54:57]
	v_mfma_f32_16x16x32_bf16 v[46:49], v[152:155], v[204:207], v[46:49]
	v_mfma_f32_16x16x32_bf16 v[38:41], v[144:147], v[214:217], v[38:41]
	v_mfma_f32_16x16x32_bf16 v[30:33], v[152:155], v[214:217], v[30:33]
	v_mfma_f32_16x16x32_bf16 v[22:25], v[144:147], v[222:225], v[22:25]
	v_mfma_f32_16x16x32_bf16 v[14:17], v[152:155], v[222:225], v[14:17]
	s_setprio 0
	s_setprio 1
	v_mfma_f32_16x16x32_bf16 v[50:53], v[156:159], v[182:185], v[50:53]
	v_mfma_f32_16x16x32_bf16 v[42:45], v[174:177], v[182:185], v[42:45]
	v_mfma_f32_16x16x32_bf16 v[34:37], v[156:159], v[190:193], v[34:37]
	v_mfma_f32_16x16x32_bf16 v[26:29], v[174:177], v[190:193], v[26:29]
	v_mfma_f32_16x16x32_bf16 v[18:21], v[156:159], v[210:213], v[18:21]
	v_mfma_f32_16x16x32_bf16 v[10:13], v[174:177], v[210:213], v[10:13]
	v_mfma_f32_16x16x32_bf16 v[6:9], v[156:159], v[218:221], v[6:9]
	v_mfma_f32_16x16x32_bf16 v[2:5], v[174:177], v[218:221], v[2:5]
	v_mfma_f32_16x16x32_bf16 v[50:53], v[170:173], v[186:189], v[50:53]
	v_mfma_f32_16x16x32_bf16 v[42:45], v[178:181], v[186:189], v[42:45]
	v_mfma_f32_16x16x32_bf16 v[34:37], v[170:173], v[204:207], v[34:37]
	v_mfma_f32_16x16x32_bf16 v[26:29], v[178:181], v[204:207], v[26:29]
	v_mfma_f32_16x16x32_bf16 v[18:21], v[170:173], v[214:217], v[18:21]
	v_mfma_f32_16x16x32_bf16 v[10:13], v[178:181], v[214:217], v[10:13]
	v_mfma_f32_16x16x32_bf16 v[6:9], v[170:173], v[222:225], v[6:9]
	v_mfma_f32_16x16x32_bf16 v[2:5], v[178:181], v[222:225], v[2:5]
	s_barrier
	s_setprio 0
	s_add_i32 s46, s46, 2
	s_add_u32 s44, s44, 0x100
	s_addc_u32 s45, s45, 0
	s_add_u32 s60, s60, 0x100
	s_addc_u32 s61, s61, 0
	s_cmp_gt_u32 s46, 13
	s_cbranch_scc0 .LBB0_559
	s_and_b64 vcc, exec, s[4:5]
	s_cbranch_vccz .LBB0_562
	s_barrier

; #define PG8_STAGE(bufoff, gbase, voff) do { _Pragma("unroll") for (int _i = 0; _i < 2; ++_i) \
;         __builtin_amdgcn_global_load_lds((const gunsigned*)((const gchar*)(gbase) + (voff)[_i]), (LAS unsigned*)(lds + (bufoff) + ldsw + _i * 8192), 16, 0, 0); } while (0)
; #define PG8_LDA(dst, b, h) do { _Pragma("unroll") for (int m = 0; m < 4; ++m) _Pragma("unroll") for (int k = 0; k < 2; ++k) dst[m][k] = *(const LAS bf16x8*)(lds + PG8_SA(b, h) + aoff + m * 2048 + k * 1024); } while (0)
; #define PG8_LDB(dst, b, h) do { _Pragma("unroll") for (int n = 0; n < 2; ++n) _Pragma("unroll") for (int k = 0; k < 2; ++k) dst[n][k] = *(const LAS bf16x8*)(lds + PG8_SB(b, h) + boff + n * 2048 + k * 1024); } while (0)
; #define PG8_MMA(ai, bj, At, Bt) do { __builtin_amdgcn_s_setprio(1); _Pragma("unroll") for (int m = 0; m < 4; ++m) _Pragma("unroll") for (int n = 0; n < 2; ++n) _Pragma("unroll") for (int k = 0; k < 2; ++k) \
;         acc[ai][bj][m][n] = __builtin_amdgcn_mfma_f32_16x16x32_bf16(Bt[n][k], At[m][k], acc[ai][bj][m][n], 0, 0, 0); __builtin_amdgcn_s_setprio(0); } while (0)
; #define PG8_WAIT_V(n) asm volatile("s_waitcnt vmcnt(" #n ")" ::: "memory")
; #define PG8_WAIT_L(n) asm volatile("s_waitcnt lgkmcnt(" #n ")" ::: "memory")
; #define PG8_BAR __builtin_amdgcn_s_barrier()
; #define PG8_SCHED __builtin_amdgcn_sched_barrier(0)
; template <class Epi, class Sched>
; __device__ __forceinline__ void gemm_phase(LAS unsigned char* lds, const int tid, const Gemm g, const Sched& S, const Epi& E) {
;     ...
;         for (int t = 0; t < nt; t += 2) {
;             const bool last = (t == nt - 2);
;             const gchar* a1 = cA + (size_t)(t + 1) * kstep;
;             const gchar* a2 = last ? nA : cA + (size_t)(t + 2) * kstep; const gchar* b2 = last ? nB : cB + (size_t)(t + 2) * kstep;
;             const gchar* a3 = a2 + kstep; const gchar* b3 = b2 + kstep;
;             PG8_LDB(B0, 0, 0); PG8_LDB(B1, 0, 1); PG8_SCHED; PG8_LDA(At, 0, 0); PG8_STAGE(PG8_SA(1, 1), a1 + hstep, voffA);
;             PG8_WAIT_V(8); PG8_WAIT_L(0); PG8_BAR; PG8_MMA(0, 0, At, B0); PG8_MMA(0, 1, At, B1); PG8_BAR; PG8_SCHED;
;             PG8_LDA(At, 0, 1); PG8_STAGE(PG8_SB(0, 0), b2, voffB); PG8_STAGE(PG8_SB(0, 1), b2 + hstep, voffB); PG8_STAGE(PG8_SA(0, 0), a2, voffA);
;             PG8_WAIT_V(8); PG8_WAIT_L(0); PG8_BAR; PG8_MMA(1, 0, At, B0); PG8_MMA(1, 1, At, B1); PG8_BAR; PG8_SCHED;
.LBB0_598:
	s_add_u32 s20, s62, 0x100
	s_addc_u32 s21, s63, 0
	s_add_i32 s29, 0, 0x10000
	s_cmp_eq_u32 s45, 40
	s_cselect_b32 s73, s9, s21
	s_cselect_b32 s72, s8, s20
	s_cselect_b32 s67, s61, s44
	s_cselect_b32 s66, s60, s31
	s_add_i32 s48, 0, 0x14000
	v_add_u32_e32 v142, s29, v210
	v_add_u32_e32 v158, s48, v210
	ds_read_b128 v[130:133], v142
	ds_read_b128 v[134:137], v142 offset:1024
	ds_read_b128 v[138:141], v142 offset:2048
	ds_read_b128 v[142:145], v142 offset:3072
	ds_read_b128 v[146:149], v158
	ds_read_b128 v[150:153], v158 offset:1024
	ds_read_b128 v[154:157], v158 offset:2048
	ds_read_b128 v[158:161], v158 offset:3072
	s_add_i32 m0, s34, 0xc000
	ds_read_b128 v[162:165], v214
	ds_read_b128 v[166:169], v214 offset:1024
	ds_read_b128 v[170:173], v214 offset:2048
	ds_read_b128 v[174:177], v214 offset:3072
	ds_read_b128 v[188:191], v214 offset:4096
	ds_read_b128 v[192:195], v214 offset:5120
	ds_read_b128 v[204:207], v214 offset:6144
	ds_read_b128 v[216:219], v214 offset:7168
	global_load_lds_dwordx4 v186, s[62:63]
	s_add_i32 m0, s34, 0xe000
	s_nop 0
	global_load_lds_dwordx4 v184, s[62:63]
	s_waitcnt vmcnt(8)
	s_waitcnt lgkmcnt(0)
	s_setprio 1
	s_barrier
	v_mfma_f32_16x16x32_bf16 v[126:129], v[130:133], v[162:165], v[126:129]
	v_mfma_f32_16x16x32_bf16 v[122:125], v[138:141], v[162:165], v[122:125]
	v_mfma_f32_16x16x32_bf16 v[110:113], v[130:133], v[170:173], v[110:113]
	v_mfma_f32_16x16x32_bf16 v[106:109], v[138:141], v[170:173], v[106:109]
	v_mfma_f32_16x16x32_bf16 v[94:97], v[130:133], v[188:191], v[94:97]
	v_mfma_f32_16x16x32_bf16 v[90:93], v[138:141], v[188:191], v[90:93]
	v_mfma_f32_16x16x32_bf16 v[78:81], v[130:133], v[204:207], v[78:81]
	v_mfma_f32_16x16x32_bf16 v[74:77], v[138:141], v[204:207], v[74:77]
	v_mfma_f32_16x16x32_bf16 v[126:129], v[134:137], v[166:169], v[126:129]
	v_mfma_f32_16x16x32_bf16 v[122:125], v[142:145], v[166:169], v[122:125]
	v_mfma_f32_16x16x32_bf16 v[110:113], v[134:137], v[174:177], v[110:113]
	v_mfma_f32_16x16x32_bf16 v[106:109], v[142:145], v[174:177], v[106:109]
	v_mfma_f32_16x16x32_bf16 v[94:97], v[134:137], v[192:195], v[94:97]
	v_mfma_f32_16x16x32_bf16 v[90:93], v[142:145], v[192:195], v[90:93]
	v_mfma_f32_16x16x32_bf16 v[78:81], v[134:137], v[216:219], v[78:81]
	v_mfma_f32_16x16x32_bf16 v[74:77], v[142:145], v[216:219], v[74:77]
	s_setprio 0
	s_setprio 1
	v_mfma_f32_16x16x32_bf16 v[118:121], v[146:149], v[162:165], v[118:121]
	v_mfma_f32_16x16x32_bf16 v[114:117], v[154:157], v[162:165], v[114:117]
	v_mfma_f32_16x16x32_bf16 v[102:105], v[146:149], v[170:173], v[102:105]
	v_mfma_f32_16x16x32_bf16 v[98:101], v[154:157], v[170:173], v[98:101]
	v_mfma_f32_16x16x32_bf16 v[86:89], v[146:149], v[188:191], v[86:89]
	v_mfma_f32_16x16x32_bf16 v[82:85], v[154:157], v[188:191], v[82:85]
	v_mfma_f32_16x16x32_bf16 v[70:73], v[146:149], v[204:207], v[70:73]
	v_mfma_f32_16x16x32_bf16 v[66:69], v[154:157], v[204:207], v[66:69]
	v_mfma_f32_16x16x32_bf16 v[118:121], v[150:153], v[166:169], v[118:121]
	v_mfma_f32_16x16x32_bf16 v[114:117], v[158:161], v[166:169], v[114:117]
	v_mfma_f32_16x16x32_bf16 v[102:105], v[150:153], v[174:177], v[102:105]
	v_mfma_f32_16x16x32_bf16 v[98:101], v[158:161], v[174:177], v[98:101]
	v_mfma_f32_16x16x32_bf16 v[86:89], v[150:153], v[192:195], v[86:89]
	v_mfma_f32_16x16x32_bf16 v[82:85], v[158:161], v[192:195], v[82:85]
	v_mfma_f32_16x16x32_bf16 v[70:73], v[150:153], v[216:219], v[70:73]
	v_mfma_f32_16x16x32_bf16 v[66:69], v[158:161], v[216:219], v[66:69]
	s_barrier
	s_setprio 0
	s_add_i32 s29, s29, s15
	s_mov_b32 m0, s29
	ds_read_b128 v[162:165], v214 offset:16384
	ds_read_b128 v[166:169], v214 offset:17408
	ds_read_b128 v[170:173], v214 offset:18432
	ds_read_b128 v[174:177], v214 offset:19456
	ds_read_b128 v[188:191], v214 offset:20480
	ds_read_b128 v[192:195], v214 offset:21504
	ds_read_b128 v[204:207], v214 offset:22528
	ds_read_b128 v[216:219], v214 offset:23552
	global_load_lds_dwordx4 v0, s[66:67]
	s_add_i32 m0, s29, 0x2000
	s_add_u32 s46, s66, 0xb0000
	s_addc_u32 s47, s67, 0
	s_add_i32 s29, s48, s15
	global_load_lds_dwordx4 v182, s[66:67]
	s_mov_b32 m0, s29
	s_nop 0
	global_load_lds_dwordx4 v0, s[46:47]
	s_add_i32 m0, s29, 0x2000
	s_nop 0
	global_load_lds_dwordx4 v182, s[46:47]
	s_mov_b32 m0, s34
	s_nop 0
	global_load_lds_dwordx4 v178, s[72:73]
	s_mov_b32 m0, s12
	s_nop 0
	global_load_lds_dwordx4 v180, s[72:73]
	s_waitcnt vmcnt(8)
	s_waitcnt lgkmcnt(0)
	s_setprio 1
	s_barrier
	v_mfma_f32_16x16x32_bf16 v[62:65], v[130:133], v[162:165], v[62:65]
	v_mfma_f32_16x16x32_bf16 v[58:61], v[138:141], v[162:165], v[58:61]
	v_mfma_f32_16x16x32_bf16 v[46:49], v[130:133], v[170:173], v[46:49]
	v_mfma_f32_16x16x32_bf16 v[42:45], v[138:141], v[170:173], v[42:45]
	v_mfma_f32_16x16x32_bf16 v[30:33], v[130:133], v[188:191], v[30:33]
	v_mfma_f32_16x16x32_bf16 v[26:29], v[138:141], v[188:191], v[26:29]
	v_mfma_f32_16x16x32_bf16 v[14:17], v[130:133], v[204:207], v[14:17]
	v_mfma_f32_16x16x32_bf16 v[10:13], v[138:141], v[204:207], v[10:13]
	v_mfma_f32_16x16x32_bf16 v[62:65], v[134:137], v[166:169], v[62:65]
	v_mfma_f32_16x16x32_bf16 v[58:61], v[142:145], v[166:169], v[58:61]
	v_mfma_f32_16x16x32_bf16 v[46:49], v[134:137], v[174:177], v[46:49]
	v_mfma_f32_16x16x32_bf16 v[42:45], v[142:145], v[174:177], v[42:45]
	v_mfma_f32_16x16x32_bf16 v[30:33], v[134:137], v[192:195], v[30:33]
	v_mfma_f32_16x16x32_bf16 v[26:29], v[142:145], v[192:195], v[26:29]
	v_mfma_f32_16x16x32_bf16 v[14:17], v[134:137], v[216:219], v[14:17]
	v_mfma_f32_16x16x32_bf16 v[10:13], v[142:145], v[216:219], v[10:13]
	s_setprio 0
	s_setprio 1
	v_mfma_f32_16x16x32_bf16 v[54:57], v[146:149], v[162:165], v[54:57]
	v_mfma_f32_16x16x32_bf16 v[50:53], v[154:157], v[162:165], v[50:53]
	v_mfma_f32_16x16x32_bf16 v[38:41], v[146:149], v[170:173], v[38:41]
	v_mfma_f32_16x16x32_bf16 v[34:37], v[154:157], v[170:173], v[34:37]
	v_mfma_f32_16x16x32_bf16 v[22:25], v[146:149], v[188:191], v[22:25]
	v_mfma_f32_16x16x32_bf16 v[18:21], v[154:157], v[188:191], v[18:21]
	v_mfma_f32_16x16x32_bf16 v[6:9], v[146:149], v[204:207], v[6:9]
	v_mfma_f32_16x16x32_bf16 v[2:5], v[154:157], v[204:207], v[2:5]
	v_mfma_f32_16x16x32_bf16 v[54:57], v[150:153], v[166:169], v[54:57]
	v_mfma_f32_16x16x32_bf16 v[50:53], v[158:161], v[166:169], v[50:53]
	v_mfma_f32_16x16x32_bf16 v[38:41], v[150:153], v[174:177], v[38:41]
	v_mfma_f32_16x16x32_bf16 v[34:37], v[158:161], v[174:177], v[34:37]
	v_mfma_f32_16x16x32_bf16 v[22:25], v[150:153], v[192:195], v[22:25]
	v_mfma_f32_16x16x32_bf16 v[18:21], v[158:161], v[192:195], v[18:21]
	v_mfma_f32_16x16x32_bf16 v[6:9], v[150:153], v[216:219], v[6:9]
	v_mfma_f32_16x16x32_bf16 v[2:5], v[158:161], v[216:219], v[2:5]
	s_barrier
; #define PG8_STAGE(bufoff, gbase, voff) do { _Pragma("unroll") for (int _i = 0; _i < 2; ++_i) \
;         __builtin_amdgcn_global_load_lds((const gunsigned*)((const gchar*)(gbase) + (voff)[_i]), (LAS unsigned*)(lds + (bufoff) + ldsw + _i * 8192), 16, 0, 0); } while (0)
; #define PG8_LDA(dst, b, h) do { _Pragma("unroll") for (int m = 0; m < 4; ++m) _Pragma("unroll") for (int k = 0; k < 2; ++k) dst[m][k] = *(const LAS bf16x8*)(lds + PG8_SA(b, h) + aoff + m * 2048 + k * 1024); } while (0)
; #define PG8_LDB(dst, b, h) do { _Pragma("unroll") for (int n = 0; n < 2; ++n) _Pragma("unroll") for (int k = 0; k < 2; ++k) dst[n][k] = *(const LAS bf16x8*)(lds + PG8_SB(b, h) + boff + n * 2048 + k * 1024); } while (0)
; #define PG8_MMA(ai, bj, At, Bt) do { __builtin_amdgcn_s_setprio(1); _Pragma("unroll") for (int m = 0; m < 4; ++m) _Pragma("unroll") for (int n = 0; n < 2; ++n) _Pragma("unroll") for (int k = 0; k < 2; ++k) \
;         acc[ai][bj][m][n] = __builtin_amdgcn_mfma_f32_16x16x32_bf16(Bt[n][k], At[m][k], acc[ai][bj][m][n], 0, 0, 0); __builtin_amdgcn_s_setprio(0); } while (0)
; #define PG8_WAIT_V(n) asm volatile("s_waitcnt vmcnt(" #n ")" ::: "memory")
; #define PG8_WAIT_L(n) asm volatile("s_waitcnt lgkmcnt(" #n ")" ::: "memory")
; #define PG8_BAR __builtin_amdgcn_s_barrier()
; #define PG8_SCHED __builtin_amdgcn_sched_barrier(0)
; template <class Epi, class Sched>
; __device__ __forceinline__ void gemm_phase(LAS unsigned char* lds, const int tid, const Gemm g, const Sched& S, const Epi& E) {
;     ...
;             PG8_LDB(B0, 1, 0); PG8_LDB(B1, 1, 1); PG8_SCHED; PG8_LDA(At, 1, 0); PG8_STAGE(PG8_SA(0, 1), a2 + hstep, voffA);
;             PG8_WAIT_V(8); PG8_WAIT_L(0); PG8_BAR; PG8_MMA(0, 0, At, B0); PG8_MMA(0, 1, At, B1); PG8_BAR; PG8_SCHED;
;             PG8_LDA(At, 1, 1); PG8_STAGE(PG8_SB(1, 0), b3, voffB); PG8_STAGE(PG8_SB(1, 1), b3 + hstep, voffB); PG8_STAGE(PG8_SA(1, 0), a3, voffA);
;             PG8_WAIT_V(8); PG8_WAIT_L(0); PG8_BAR; PG8_MMA(1, 0, At, B0); PG8_MMA(1, 1, At, B1); PG8_BAR; PG8_SCHED;
;         }
;         if (wr == 0) PG8_BAR;
	s_setprio 0
	s_add_i32 s29, 0, 0x18000
	s_add_i32 s48, 0, 0x1c000
	v_add_u32_e32 v142, s29, v210
	v_add_u32_e32 v158, s48, v210
	ds_read_b128 v[130:133], v142
	ds_read_b128 v[134:137], v142 offset:1024
	ds_read_b128 v[138:141], v142 offset:2048
	ds_read_b128 v[142:145], v142 offset:3072
	ds_read_b128 v[146:149], v158
	ds_read_b128 v[150:153], v158 offset:1024
	ds_read_b128 v[154:157], v158 offset:2048
	ds_read_b128 v[158:161], v158 offset:3072
	s_add_u32 s46, s72, 0xb0000
	s_addc_u32 s47, s73, 0
	s_mov_b32 m0, s35
	ds_read_b128 v[162:165], v214 offset:32768
	ds_read_b128 v[166:169], v214 offset:33792
	ds_read_b128 v[170:173], v214 offset:34816
	ds_read_b128 v[174:177], v214 offset:35840
	ds_read_b128 v[188:191], v214 offset:36864
	ds_read_b128 v[192:195], v214 offset:37888
	ds_read_b128 v[204:207], v214 offset:38912
	ds_read_b128 v[216:219], v214 offset:39936
	global_load_lds_dwordx4 v178, s[46:47]
	s_mov_b32 m0, s36
	s_nop 0
	global_load_lds_dwordx4 v180, s[46:47]
	s_waitcnt vmcnt(8)
	s_waitcnt lgkmcnt(0)
	s_setprio 1
	s_barrier
	v_mfma_f32_16x16x32_bf16 v[126:129], v[130:133], v[162:165], v[126:129]
	v_mfma_f32_16x16x32_bf16 v[122:125], v[138:141], v[162:165], v[122:125]
	v_mfma_f32_16x16x32_bf16 v[110:113], v[130:133], v[170:173], v[110:113]
	v_mfma_f32_16x16x32_bf16 v[106:109], v[138:141], v[170:173], v[106:109]
	v_mfma_f32_16x16x32_bf16 v[94:97], v[130:133], v[188:191], v[94:97]
	v_mfma_f32_16x16x32_bf16 v[90:93], v[138:141], v[188:191], v[90:93]
	v_mfma_f32_16x16x32_bf16 v[78:81], v[130:133], v[204:207], v[78:81]
	v_mfma_f32_16x16x32_bf16 v[74:77], v[138:141], v[204:207], v[74:77]
	v_mfma_f32_16x16x32_bf16 v[126:129], v[134:137], v[166:169], v[126:129]
	v_mfma_f32_16x16x32_bf16 v[122:125], v[142:145], v[166:169], v[122:125]
	v_mfma_f32_16x16x32_bf16 v[110:113], v[134:137], v[174:177], v[110:113]
	v_mfma_f32_16x16x32_bf16 v[106:109], v[142:145], v[174:177], v[106:109]
	v_mfma_f32_16x16x32_bf16 v[94:97], v[134:137], v[192:195], v[94:97]
	v_mfma_f32_16x16x32_bf16 v[90:93], v[142:145], v[192:195], v[90:93]
	v_mfma_f32_16x16x32_bf16 v[78:81], v[134:137], v[216:219], v[78:81]
	v_mfma_f32_16x16x32_bf16 v[74:77], v[142:145], v[216:219], v[74:77]
	s_setprio 0
	s_setprio 1
	v_mfma_f32_16x16x32_bf16 v[118:121], v[146:149], v[162:165], v[118:121]
	v_mfma_f32_16x16x32_bf16 v[114:117], v[154:157], v[162:165], v[114:117]
	v_mfma_f32_16x16x32_bf16 v[102:105], v[146:149], v[170:173], v[102:105]
	v_mfma_f32_16x16x32_bf16 v[98:101], v[154:157], v[170:173], v[98:101]
	v_mfma_f32_16x16x32_bf16 v[86:89], v[146:149], v[188:191], v[86:89]
	v_mfma_f32_16x16x32_bf16 v[82:85], v[154:157], v[188:191], v[82:85]
	v_mfma_f32_16x16x32_bf16 v[70:73], v[146:149], v[204:207], v[70:73]
	v_mfma_f32_16x16x32_bf16 v[66:69], v[154:157], v[204:207], v[66:69]
	v_mfma_f32_16x16x32_bf16 v[118:121], v[150:153], v[166:169], v[118:121]
	v_mfma_f32_16x16x32_bf16 v[114:117], v[158:161], v[166:169], v[114:117]
	v_mfma_f32_16x16x32_bf16 v[102:105], v[150:153], v[174:177], v[102:105]
	v_mfma_f32_16x16x32_bf16 v[98:101], v[158:161], v[174:177], v[98:101]
	v_mfma_f32_16x16x32_bf16 v[86:89], v[150:153], v[192:195], v[86:89]
	v_mfma_f32_16x16x32_bf16 v[82:85], v[158:161], v[192:195], v[82:85]
	v_mfma_f32_16x16x32_bf16 v[70:73], v[150:153], v[216:219], v[70:73]
	v_mfma_f32_16x16x32_bf16 v[66:69], v[158:161], v[216:219], v[66:69]
	s_barrier
	s_setprio 0
	s_add_i32 s29, s29, s15
	s_mov_b32 m0, s29
	ds_read_b128 v[162:165], v214 offset:49152
	ds_read_b128 v[166:169], v214 offset:50176
	ds_read_b128 v[170:173], v214 offset:51200
	ds_read_b128 v[174:177], v214 offset:52224
	ds_read_b128 v[188:191], v214 offset:53248
	ds_read_b128 v[192:195], v214 offset:54272
	ds_read_b128 v[204:207], v214 offset:55296
	ds_read_b128 v[216:219], v214 offset:56320
	global_load_lds_dwordx4 v221, s[66:67]
	s_add_i32 m0, s29, 0x2000
	s_add_u32 s46, s66, 0xb0080
	s_addc_u32 s47, s67, 0
	s_add_i32 s29, s48, s15
	global_load_lds_dwordx4 v223, s[66:67]
	s_mov_b32 m0, s29
	s_nop 0
	global_load_lds_dwordx4 v0, s[46:47]
	s_add_i32 m0, s29, 0x2000
	s_nop 0
	global_load_lds_dwordx4 v182, s[46:47]
	s_mov_b32 m0, s37
	s_nop 0
	global_load_lds_dwordx4 v225, s[72:73]
	s_mov_b32 m0, s38
	s_nop 0
	global_load_lds_dwordx4 v227, s[72:73]
	s_waitcnt vmcnt(8)
	s_waitcnt lgkmcnt(0)
	s_setprio 1
	s_barrier
	v_mfma_f32_16x16x32_bf16 v[62:65], v[130:133], v[162:165], v[62:65]
	v_mfma_f32_16x16x32_bf16 v[58:61], v[138:141], v[162:165], v[58:61]
	v_mfma_f32_16x16x32_bf16 v[46:49], v[130:133], v[170:173], v[46:49]
	v_mfma_f32_16x16x32_bf16 v[42:45], v[138:141], v[170:173], v[42:45]
	v_mfma_f32_16x16x32_bf16 v[30:33], v[130:133], v[188:191], v[30:33]
	v_mfma_f32_16x16x32_bf16 v[26:29], v[138:141], v[188:191], v[26:29]
	v_mfma_f32_16x16x32_bf16 v[14:17], v[130:133], v[204:207], v[14:17]
	v_mfma_f32_16x16x32_bf16 v[10:13], v[138:141], v[204:207], v[10:13]
	v_mfma_f32_16x16x32_bf16 v[62:65], v[134:137], v[166:169], v[62:65]
	v_mfma_f32_16x16x32_bf16 v[58:61], v[142:145], v[166:169], v[58:61]
	v_mfma_f32_16x16x32_bf16 v[46:49], v[134:137], v[174:177], v[46:49]
	v_mfma_f32_16x16x32_bf16 v[42:45], v[142:145], v[174:177], v[42:45]
	v_mfma_f32_16x16x32_bf16 v[30:33], v[134:137], v[192:195], v[30:33]
	v_mfma_f32_16x16x32_bf16 v[26:29], v[142:145], v[192:195], v[26:29]
	v_mfma_f32_16x16x32_bf16 v[14:17], v[134:137], v[216:219], v[14:17]
	v_mfma_f32_16x16x32_bf16 v[10:13], v[142:145], v[216:219], v[10:13]
	s_setprio 0
	s_setprio 1
	v_mfma_f32_16x16x32_bf16 v[54:57], v[146:149], v[162:165], v[54:57]
	v_mfma_f32_16x16x32_bf16 v[50:53], v[154:157], v[162:165], v[50:53]
	v_mfma_f32_16x16x32_bf16 v[38:41], v[146:149], v[170:173], v[38:41]
	v_mfma_f32_16x16x32_bf16 v[34:37], v[154:157], v[170:173], v[34:37]
	v_mfma_f32_16x16x32_bf16 v[22:25], v[146:149], v[188:191], v[22:25]
	v_mfma_f32_16x16x32_bf16 v[18:21], v[154:157], v[188:191], v[18:21]
	v_mfma_f32_16x16x32_bf16 v[6:9], v[146:149], v[204:207], v[6:9]
	v_mfma_f32_16x16x32_bf16 v[2:5], v[154:157], v[204:207], v[2:5]
	v_mfma_f32_16x16x32_bf16 v[54:57], v[150:153], v[166:169], v[54:57]
	v_mfma_f32_16x16x32_bf16 v[50:53], v[158:161], v[166:169], v[50:53]
	v_mfma_f32_16x16x32_bf16 v[38:41], v[150:153], v[174:177], v[38:41]
	v_mfma_f32_16x16x32_bf16 v[34:37], v[158:161], v[174:177], v[34:37]
	v_mfma_f32_16x16x32_bf16 v[22:25], v[150:153], v[192:195], v[22:25]
	v_mfma_f32_16x16x32_bf16 v[18:21], v[158:161], v[192:195], v[18:21]
	v_mfma_f32_16x16x32_bf16 v[6:9], v[150:153], v[216:219], v[6:9]
	v_mfma_f32_16x16x32_bf16 v[2:5], v[158:161], v[216:219], v[2:5]
	s_barrier
	s_setprio 0
	s_add_i32 s45, s45, 2
	s_add_u32 s31, s31, 0x100
	s_addc_u32 s44, s44, 0
	s_cmp_gt_u32 s45, 41
	s_mov_b64 s[62:63], s[20:21]
	s_cbranch_scc0 .LBB0_598
	s_and_b64 vcc, exec, s[58:59]
	s_cbranch_vccz .LBB0_601
	s_barrier

; #define PG8_STAGE(bufoff, gbase, voff) do { _Pragma("unroll") for (int _i = 0; _i < 2; ++_i) \
;         __builtin_amdgcn_global_load_lds((const gunsigned*)((const gchar*)(gbase) + (voff)[_i]), (LAS unsigned*)(lds + (bufoff) + ldsw + _i * 8192), 16, 0, 0); } while (0)
; #define PG8_LDA(dst, b, h) do { _Pragma("unroll") for (int m = 0; m < 4; ++m) _Pragma("unroll") for (int k = 0; k < 2; ++k) dst[m][k] = *(const LAS bf16x8*)(lds + PG8_SA(b, h) + aoff + m * 2048 + k * 1024); } while (0)
; #define PG8_LDB(dst, b, h) do { _Pragma("unroll") for (int n = 0; n < 2; ++n) _Pragma("unroll") for (int k = 0; k < 2; ++k) dst[n][k] = *(const LAS bf16x8*)(lds + PG8_SB(b, h) + boff + n * 2048 + k * 1024); } while (0)
; #define PG8_MMA(ai, bj, At, Bt) do { __builtin_amdgcn_s_setprio(1); _Pragma("unroll") for (int m = 0; m < 4; ++m) _Pragma("unroll") for (int n = 0; n < 2; ++n) _Pragma("unroll") for (int k = 0; k < 2; ++k) \
;         acc[ai][bj][m][n] = __builtin_amdgcn_mfma_f32_16x16x32_bf16(Bt[n][k], At[m][k], acc[ai][bj][m][n], 0, 0, 0); __builtin_amdgcn_s_setprio(0); } while (0)
; #define PG8_WAIT_V(n) asm volatile("s_waitcnt vmcnt(" #n ")" ::: "memory")
; #define PG8_WAIT_L(n) asm volatile("s_waitcnt lgkmcnt(" #n ")" ::: "memory")
; #define PG8_BAR __builtin_amdgcn_s_barrier()
; #define PG8_SCHED __builtin_amdgcn_sched_barrier(0)
; template <class Epi, class Sched>
; __device__ __forceinline__ void gemm_phase(LAS unsigned char* lds, const int tid, const Gemm g, const Sched& S, const Epi& E) {
;     ...
;         for (int t = 0; t < nt; t += 2) {
;             const bool last = (t == nt - 2);
;             const gchar* a1 = cA + (size_t)(t + 1) * kstep;
;             const gchar* a2 = last ? nA : cA + (size_t)(t + 2) * kstep; const gchar* b2 = last ? nB : cB + (size_t)(t + 2) * kstep;
;             const gchar* a3 = a2 + kstep; const gchar* b3 = b2 + kstep;
;             PG8_LDB(B0, 0, 0); PG8_LDB(B1, 0, 1); PG8_SCHED; PG8_LDA(At, 0, 0); PG8_STAGE(PG8_SA(1, 1), a1 + hstep, voffA);
;             PG8_WAIT_V(8); PG8_WAIT_L(0); PG8_BAR; PG8_MMA(0, 0, At, B0); PG8_MMA(0, 1, At, B1); PG8_BAR; PG8_SCHED;
;             PG8_LDA(At, 0, 1); PG8_STAGE(PG8_SB(0, 0), b2, voffB); PG8_STAGE(PG8_SB(0, 1), b2 + hstep, voffB); PG8_STAGE(PG8_SA(0, 0), a2, voffA);
;             PG8_WAIT_V(8); PG8_WAIT_L(0); PG8_BAR; PG8_MMA(1, 0, At, B0); PG8_MMA(1, 1, At, B1); PG8_BAR; PG8_SCHED;
.LBB0_647:
	s_add_u32 s20, s58, 0xfffc0080
	s_addc_u32 s21, s59, -1
	s_add_i32 s42, 0, 0x10000
	s_cmp_eq_u32 s41, 12
	s_cselect_b32 s61, s9, s21
	s_cselect_b32 s60, s37, s20
	v_add_u32_e32 v140, s42, v143
	s_cselect_b32 s21, s7, s40
	s_cselect_b32 s20, s38, s39
	s_add_i32 s44, 0, 0x14000
	ds_read_b128 v[146:149], v140
	ds_read_b128 v[150:153], v140 offset:1024
	ds_read_b128 v[154:157], v140 offset:2048
	ds_read_b128 v[158:161], v140 offset:3072
	v_add_u32_e32 v140, s44, v143
	ds_read_b128 v[162:165], v140
	ds_read_b128 v[166:169], v140 offset:1024
	ds_read_b128 v[170:173], v140 offset:2048
	ds_read_b128 v[174:177], v140 offset:3072
	s_add_i32 m0, s23, 0xc000
	ds_read_b128 v[178:181], v145
	ds_read_b128 v[182:185], v145 offset:1024
	ds_read_b128 v[186:189], v145 offset:2048
	ds_read_b128 v[190:193], v145 offset:3072
	ds_read_b128 v[204:207], v145 offset:4096
	ds_read_b128 v[208:211], v145 offset:5120
	ds_read_b128 v[212:215], v145 offset:6144
	ds_read_b128 v[216:219], v145 offset:7168
	global_load_lds_dwordx4 v138, s[58:59]
	s_add_i32 m0, s23, 0xe000
	s_nop 0
	global_load_lds_dwordx4 v136, s[58:59]
	s_waitcnt vmcnt(8)
	s_waitcnt lgkmcnt(0)
	s_setprio 1
	s_barrier
	v_mfma_f32_16x16x32_bf16 v[126:129], v[146:149], v[178:181], v[126:129]
	v_mfma_f32_16x16x32_bf16 v[122:125], v[154:157], v[178:181], v[122:125]
	v_mfma_f32_16x16x32_bf16 v[110:113], v[146:149], v[186:189], v[110:113]
	v_mfma_f32_16x16x32_bf16 v[106:109], v[154:157], v[186:189], v[106:109]
	v_mfma_f32_16x16x32_bf16 v[94:97], v[146:149], v[204:207], v[94:97]
	v_mfma_f32_16x16x32_bf16 v[90:93], v[154:157], v[204:207], v[90:93]
	v_mfma_f32_16x16x32_bf16 v[78:81], v[146:149], v[212:215], v[78:81]
	v_mfma_f32_16x16x32_bf16 v[74:77], v[154:157], v[212:215], v[74:77]
	v_mfma_f32_16x16x32_bf16 v[126:129], v[150:153], v[182:185], v[126:129]
	v_mfma_f32_16x16x32_bf16 v[122:125], v[158:161], v[182:185], v[122:125]
	v_mfma_f32_16x16x32_bf16 v[110:113], v[150:153], v[190:193], v[110:113]
	v_mfma_f32_16x16x32_bf16 v[106:109], v[158:161], v[190:193], v[106:109]
	v_mfma_f32_16x16x32_bf16 v[94:97], v[150:153], v[208:211], v[94:97]
	v_mfma_f32_16x16x32_bf16 v[90:93], v[158:161], v[208:211], v[90:93]
	v_mfma_f32_16x16x32_bf16 v[78:81], v[150:153], v[216:219], v[78:81]
	v_mfma_f32_16x16x32_bf16 v[74:77], v[158:161], v[216:219], v[74:77]
	s_setprio 0
	s_setprio 1
	v_mfma_f32_16x16x32_bf16 v[118:121], v[162:165], v[178:181], v[118:121]
	v_mfma_f32_16x16x32_bf16 v[114:117], v[170:173], v[178:181], v[114:117]
	v_mfma_f32_16x16x32_bf16 v[102:105], v[162:165], v[186:189], v[102:105]
	v_mfma_f32_16x16x32_bf16 v[98:101], v[170:173], v[186:189], v[98:101]
	v_mfma_f32_16x16x32_bf16 v[86:89], v[162:165], v[204:207], v[86:89]
	v_mfma_f32_16x16x32_bf16 v[82:85], v[170:173], v[204:207], v[82:85]
	v_mfma_f32_16x16x32_bf16 v[70:73], v[162:165], v[212:215], v[70:73]
	v_mfma_f32_16x16x32_bf16 v[66:69], v[170:173], v[212:215], v[66:69]
	v_mfma_f32_16x16x32_bf16 v[118:121], v[166:169], v[182:185], v[118:121]
	v_mfma_f32_16x16x32_bf16 v[114:117], v[174:177], v[182:185], v[114:117]
	v_mfma_f32_16x16x32_bf16 v[102:105], v[166:169], v[190:193], v[102:105]
	v_mfma_f32_16x16x32_bf16 v[98:101], v[174:177], v[190:193], v[98:101]
	v_mfma_f32_16x16x32_bf16 v[86:89], v[166:169], v[208:211], v[86:89]
	v_mfma_f32_16x16x32_bf16 v[82:85], v[174:177], v[208:211], v[82:85]
	v_mfma_f32_16x16x32_bf16 v[70:73], v[166:169], v[216:219], v[70:73]
	v_mfma_f32_16x16x32_bf16 v[66:69], v[174:177], v[216:219], v[66:69]
	s_barrier
	s_setprio 0
	s_add_i32 s42, s42, s12
	s_mov_b32 m0, s42
	ds_read_b128 v[178:181], v145 offset:16384
	ds_read_b128 v[182:185], v145 offset:17408
	ds_read_b128 v[186:189], v145 offset:18432
	ds_read_b128 v[190:193], v145 offset:19456
	ds_read_b128 v[204:207], v145 offset:20480
	ds_read_b128 v[208:211], v145 offset:21504
	ds_read_b128 v[212:215], v145 offset:22528
	ds_read_b128 v[216:219], v145 offset:23552
	global_load_lds_dwordx4 v0, s[20:21]
	s_add_i32 m0, s42, 0x2000
	s_add_u32 s42, s20, 0x40000
	s_addc_u32 s43, s21, 0
	s_add_i32 s44, s44, s12
	global_load_lds_dwordx4 v130, s[20:21]
	s_mov_b32 m0, s44
	s_nop 0
	global_load_lds_dwordx4 v0, s[42:43]
	s_add_i32 m0, s44, 0x2000
	s_nop 0
	global_load_lds_dwordx4 v130, s[42:43]
	s_mov_b32 m0, s23
	s_nop 0
	global_load_lds_dwordx4 v134, s[60:61]
	s_mov_b32 m0, s24
	s_nop 0
	global_load_lds_dwordx4 v132, s[60:61]
	s_waitcnt vmcnt(8)
	s_waitcnt lgkmcnt(0)
	s_setprio 1
	s_barrier
	v_mfma_f32_16x16x32_bf16 v[62:65], v[146:149], v[178:181], v[62:65]
	v_mfma_f32_16x16x32_bf16 v[58:61], v[154:157], v[178:181], v[58:61]
	v_mfma_f32_16x16x32_bf16 v[46:49], v[146:149], v[186:189], v[46:49]
	v_mfma_f32_16x16x32_bf16 v[42:45], v[154:157], v[186:189], v[42:45]
	v_mfma_f32_16x16x32_bf16 v[30:33], v[146:149], v[204:207], v[30:33]
	v_mfma_f32_16x16x32_bf16 v[26:29], v[154:157], v[204:207], v[26:29]
	v_mfma_f32_16x16x32_bf16 v[14:17], v[146:149], v[212:215], v[14:17]
	v_mfma_f32_16x16x32_bf16 v[10:13], v[154:157], v[212:215], v[10:13]
	v_mfma_f32_16x16x32_bf16 v[62:65], v[150:153], v[182:185], v[62:65]
	v_mfma_f32_16x16x32_bf16 v[58:61], v[158:161], v[182:185], v[58:61]
	v_mfma_f32_16x16x32_bf16 v[46:49], v[150:153], v[190:193], v[46:49]
	v_mfma_f32_16x16x32_bf16 v[42:45], v[158:161], v[190:193], v[42:45]
	v_mfma_f32_16x16x32_bf16 v[30:33], v[150:153], v[208:211], v[30:33]
	v_mfma_f32_16x16x32_bf16 v[26:29], v[158:161], v[208:211], v[26:29]
	v_mfma_f32_16x16x32_bf16 v[14:17], v[150:153], v[216:219], v[14:17]
	v_mfma_f32_16x16x32_bf16 v[10:13], v[158:161], v[216:219], v[10:13]
	s_setprio 0
	s_setprio 1
	v_mfma_f32_16x16x32_bf16 v[54:57], v[162:165], v[178:181], v[54:57]
	v_mfma_f32_16x16x32_bf16 v[50:53], v[170:173], v[178:181], v[50:53]
	v_mfma_f32_16x16x32_bf16 v[38:41], v[162:165], v[186:189], v[38:41]
	v_mfma_f32_16x16x32_bf16 v[34:37], v[170:173], v[186:189], v[34:37]
	v_mfma_f32_16x16x32_bf16 v[22:25], v[162:165], v[204:207], v[22:25]
	v_mfma_f32_16x16x32_bf16 v[18:21], v[170:173], v[204:207], v[18:21]
	v_mfma_f32_16x16x32_bf16 v[6:9], v[162:165], v[212:215], v[6:9]
	v_mfma_f32_16x16x32_bf16 v[2:5], v[170:173], v[212:215], v[2:5]
	v_mfma_f32_16x16x32_bf16 v[54:57], v[166:169], v[182:185], v[54:57]
	v_mfma_f32_16x16x32_bf16 v[50:53], v[174:177], v[182:185], v[50:53]
	v_mfma_f32_16x16x32_bf16 v[38:41], v[166:169], v[190:193], v[38:41]
	v_mfma_f32_16x16x32_bf16 v[34:37], v[174:177], v[190:193], v[34:37]
	v_mfma_f32_16x16x32_bf16 v[22:25], v[166:169], v[208:211], v[22:25]
	v_mfma_f32_16x16x32_bf16 v[18:21], v[174:177], v[208:211], v[18:21]
	v_mfma_f32_16x16x32_bf16 v[6:9], v[166:169], v[216:219], v[6:9]
	v_mfma_f32_16x16x32_bf16 v[2:5], v[174:177], v[216:219], v[2:5]
	s_barrier
; #define PG8_STAGE(bufoff, gbase, voff) do { _Pragma("unroll") for (int _i = 0; _i < 2; ++_i) \
;         __builtin_amdgcn_global_load_lds((const gunsigned*)((const gchar*)(gbase) + (voff)[_i]), (LAS unsigned*)(lds + (bufoff) + ldsw + _i * 8192), 16, 0, 0); } while (0)
; #define PG8_LDA(dst, b, h) do { _Pragma("unroll") for (int m = 0; m < 4; ++m) _Pragma("unroll") for (int k = 0; k < 2; ++k) dst[m][k] = *(const LAS bf16x8*)(lds + PG8_SA(b, h) + aoff + m * 2048 + k * 1024); } while (0)
; #define PG8_LDB(dst, b, h) do { _Pragma("unroll") for (int n = 0; n < 2; ++n) _Pragma("unroll") for (int k = 0; k < 2; ++k) dst[n][k] = *(const LAS bf16x8*)(lds + PG8_SB(b, h) + boff + n * 2048 + k * 1024); } while (0)
; #define PG8_MMA(ai, bj, At, Bt) do { __builtin_amdgcn_s_setprio(1); _Pragma("unroll") for (int m = 0; m < 4; ++m) _Pragma("unroll") for (int n = 0; n < 2; ++n) _Pragma("unroll") for (int k = 0; k < 2; ++k) \
;         acc[ai][bj][m][n] = __builtin_amdgcn_mfma_f32_16x16x32_bf16(Bt[n][k], At[m][k], acc[ai][bj][m][n], 0, 0, 0); __builtin_amdgcn_s_setprio(0); } while (0)
; #define PG8_WAIT_V(n) asm volatile("s_waitcnt vmcnt(" #n ")" ::: "memory")
; #define PG8_WAIT_L(n) asm volatile("s_waitcnt lgkmcnt(" #n ")" ::: "memory")
; #define PG8_BAR __builtin_amdgcn_s_barrier()
; #define PG8_SCHED __builtin_amdgcn_sched_barrier(0)
; template <class Epi, class Sched>
; __device__ __forceinline__ void gemm_phase(LAS unsigned char* lds, const int tid, const Gemm g, const Sched& S, const Epi& E) {
;     ...
;             PG8_LDB(B0, 1, 0); PG8_LDB(B1, 1, 1); PG8_SCHED; PG8_LDA(At, 1, 0); PG8_STAGE(PG8_SA(0, 1), a2 + hstep, voffA);
;             PG8_WAIT_V(8); PG8_WAIT_L(0); PG8_BAR; PG8_MMA(0, 0, At, B0); PG8_MMA(0, 1, At, B1); PG8_BAR; PG8_SCHED;
;             PG8_LDA(At, 1, 1); PG8_STAGE(PG8_SB(1, 0), b3, voffB); PG8_STAGE(PG8_SB(1, 1), b3 + hstep, voffB); PG8_STAGE(PG8_SA(1, 0), a3, voffA);
;             PG8_WAIT_V(8); PG8_WAIT_L(0); PG8_BAR; PG8_MMA(1, 0, At, B0); PG8_MMA(1, 1, At, B1); PG8_BAR; PG8_SCHED;
;         }
;         if (wr == 0) PG8_BAR;
	s_setprio 0
	s_add_i32 s44, 0, 0x18000
	s_add_i32 s45, 0, 0x1c000
	v_add_u32_e32 v158, s44, v143
	v_add_u32_e32 v174, s45, v143
	ds_read_b128 v[146:149], v158
	ds_read_b128 v[150:153], v158 offset:1024
	ds_read_b128 v[154:157], v158 offset:2048
	ds_read_b128 v[158:161], v158 offset:3072
	ds_read_b128 v[162:165], v174
	ds_read_b128 v[166:169], v174 offset:1024
	ds_read_b128 v[170:173], v174 offset:2048
	ds_read_b128 v[174:177], v174 offset:3072
	s_add_u32 s42, s60, 0x40000
	s_addc_u32 s43, s61, 0
	s_mov_b32 m0, s29
	ds_read_b128 v[178:181], v145 offset:32768
	ds_read_b128 v[182:185], v145 offset:33792
	ds_read_b128 v[186:189], v145 offset:34816
	ds_read_b128 v[190:193], v145 offset:35840
	ds_read_b128 v[204:207], v145 offset:36864
	ds_read_b128 v[208:211], v145 offset:37888
	ds_read_b128 v[212:215], v145 offset:38912
	ds_read_b128 v[216:219], v145 offset:39936
	global_load_lds_dwordx4 v134, s[42:43]
	s_mov_b32 m0, s30
	s_nop 0
	global_load_lds_dwordx4 v132, s[42:43]
	s_waitcnt vmcnt(8)
	s_waitcnt lgkmcnt(0)
	s_setprio 1
	s_barrier
	v_mfma_f32_16x16x32_bf16 v[126:129], v[146:149], v[178:181], v[126:129]
	v_mfma_f32_16x16x32_bf16 v[122:125], v[154:157], v[178:181], v[122:125]
	v_mfma_f32_16x16x32_bf16 v[110:113], v[146:149], v[186:189], v[110:113]
	v_mfma_f32_16x16x32_bf16 v[106:109], v[154:157], v[186:189], v[106:109]
	v_mfma_f32_16x16x32_bf16 v[94:97], v[146:149], v[204:207], v[94:97]
	v_mfma_f32_16x16x32_bf16 v[90:93], v[154:157], v[204:207], v[90:93]
	v_mfma_f32_16x16x32_bf16 v[78:81], v[146:149], v[212:215], v[78:81]
	v_mfma_f32_16x16x32_bf16 v[74:77], v[154:157], v[212:215], v[74:77]
	v_mfma_f32_16x16x32_bf16 v[126:129], v[150:153], v[182:185], v[126:129]
	v_mfma_f32_16x16x32_bf16 v[122:125], v[158:161], v[182:185], v[122:125]
	v_mfma_f32_16x16x32_bf16 v[110:113], v[150:153], v[190:193], v[110:113]
	v_mfma_f32_16x16x32_bf16 v[106:109], v[158:161], v[190:193], v[106:109]
	v_mfma_f32_16x16x32_bf16 v[94:97], v[150:153], v[208:211], v[94:97]
	v_mfma_f32_16x16x32_bf16 v[90:93], v[158:161], v[208:211], v[90:93]
	v_mfma_f32_16x16x32_bf16 v[78:81], v[150:153], v[216:219], v[78:81]
	v_mfma_f32_16x16x32_bf16 v[74:77], v[158:161], v[216:219], v[74:77]
	s_setprio 0
	s_setprio 1
	v_mfma_f32_16x16x32_bf16 v[118:121], v[162:165], v[178:181], v[118:121]
	v_mfma_f32_16x16x32_bf16 v[114:117], v[170:173], v[178:181], v[114:117]
	v_mfma_f32_16x16x32_bf16 v[102:105], v[162:165], v[186:189], v[102:105]
	v_mfma_f32_16x16x32_bf16 v[98:101], v[170:173], v[186:189], v[98:101]
	v_mfma_f32_16x16x32_bf16 v[86:89], v[162:165], v[204:207], v[86:89]
	v_mfma_f32_16x16x32_bf16 v[82:85], v[170:173], v[204:207], v[82:85]
	v_mfma_f32_16x16x32_bf16 v[70:73], v[162:165], v[212:215], v[70:73]
	v_mfma_f32_16x16x32_bf16 v[66:69], v[170:173], v[212:215], v[66:69]
	v_mfma_f32_16x16x32_bf16 v[118:121], v[166:169], v[182:185], v[118:121]
	v_mfma_f32_16x16x32_bf16 v[114:117], v[174:177], v[182:185], v[114:117]
	v_mfma_f32_16x16x32_bf16 v[102:105], v[166:169], v[190:193], v[102:105]
	v_mfma_f32_16x16x32_bf16 v[98:101], v[174:177], v[190:193], v[98:101]
	v_mfma_f32_16x16x32_bf16 v[86:89], v[166:169], v[208:211], v[86:89]
	v_mfma_f32_16x16x32_bf16 v[82:85], v[174:177], v[208:211], v[82:85]
	v_mfma_f32_16x16x32_bf16 v[70:73], v[166:169], v[216:219], v[70:73]
	v_mfma_f32_16x16x32_bf16 v[66:69], v[174:177], v[216:219], v[66:69]
	s_barrier
	s_setprio 0
	s_add_i32 s42, s44, s12
	s_mov_b32 m0, s42
	ds_read_b128 v[178:181], v145 offset:49152
	ds_read_b128 v[182:185], v145 offset:50176
	ds_read_b128 v[186:189], v145 offset:51200
	ds_read_b128 v[190:193], v145 offset:52224
	ds_read_b128 v[204:207], v145 offset:53248
	ds_read_b128 v[208:211], v145 offset:54272
	ds_read_b128 v[212:215], v145 offset:55296
	ds_read_b128 v[216:219], v145 offset:56320
	global_load_lds_dwordx4 v141, s[20:21]
	s_add_i32 m0, s42, 0x2000
	s_add_i32 s42, s45, s12
	global_load_lds_dwordx4 v195, s[20:21]
	s_add_u32 s20, s20, 0x40080
	s_addc_u32 s21, s21, 0
	s_mov_b32 m0, s42
	s_nop 0
	global_load_lds_dwordx4 v0, s[20:21]
	s_add_i32 m0, s42, 0x2000
	s_nop 0
	global_load_lds_dwordx4 v130, s[20:21]
	s_mov_b32 m0, s31
	s_nop 0
	global_load_lds_dwordx4 v221, s[60:61]
	s_mov_b32 m0, s34
	s_nop 0
	global_load_lds_dwordx4 v223, s[60:61]
	s_waitcnt vmcnt(8)
	s_waitcnt lgkmcnt(0)
	s_setprio 1
	s_barrier
	v_mfma_f32_16x16x32_bf16 v[62:65], v[146:149], v[178:181], v[62:65]
	v_mfma_f32_16x16x32_bf16 v[58:61], v[154:157], v[178:181], v[58:61]
	v_mfma_f32_16x16x32_bf16 v[46:49], v[146:149], v[186:189], v[46:49]
	v_mfma_f32_16x16x32_bf16 v[42:45], v[154:157], v[186:189], v[42:45]
	v_mfma_f32_16x16x32_bf16 v[30:33], v[146:149], v[204:207], v[30:33]
	v_mfma_f32_16x16x32_bf16 v[26:29], v[154:157], v[204:207], v[26:29]
	v_mfma_f32_16x16x32_bf16 v[14:17], v[146:149], v[212:215], v[14:17]
	v_mfma_f32_16x16x32_bf16 v[10:13], v[154:157], v[212:215], v[10:13]
	v_mfma_f32_16x16x32_bf16 v[62:65], v[150:153], v[182:185], v[62:65]
	v_mfma_f32_16x16x32_bf16 v[58:61], v[158:161], v[182:185], v[58:61]
	v_mfma_f32_16x16x32_bf16 v[46:49], v[150:153], v[190:193], v[46:49]
	v_mfma_f32_16x16x32_bf16 v[42:45], v[158:161], v[190:193], v[42:45]
	v_mfma_f32_16x16x32_bf16 v[30:33], v[150:153], v[208:211], v[30:33]
	v_mfma_f32_16x16x32_bf16 v[26:29], v[158:161], v[208:211], v[26:29]
	v_mfma_f32_16x16x32_bf16 v[14:17], v[150:153], v[216:219], v[14:17]
	v_mfma_f32_16x16x32_bf16 v[10:13], v[158:161], v[216:219], v[10:13]
	s_setprio 0
	s_setprio 1
	v_mfma_f32_16x16x32_bf16 v[54:57], v[162:165], v[178:181], v[54:57]
	v_mfma_f32_16x16x32_bf16 v[50:53], v[170:173], v[178:181], v[50:53]
	v_mfma_f32_16x16x32_bf16 v[38:41], v[162:165], v[186:189], v[38:41]
	v_mfma_f32_16x16x32_bf16 v[34:37], v[170:173], v[186:189], v[34:37]
	v_mfma_f32_16x16x32_bf16 v[22:25], v[162:165], v[204:207], v[22:25]
	v_mfma_f32_16x16x32_bf16 v[18:21], v[170:173], v[204:207], v[18:21]
	v_mfma_f32_16x16x32_bf16 v[6:9], v[162:165], v[212:215], v[6:9]
	v_mfma_f32_16x16x32_bf16 v[2:5], v[170:173], v[212:215], v[2:5]
	v_mfma_f32_16x16x32_bf16 v[54:57], v[166:169], v[182:185], v[54:57]
	v_mfma_f32_16x16x32_bf16 v[50:53], v[174:177], v[182:185], v[50:53]
	v_mfma_f32_16x16x32_bf16 v[38:41], v[166:169], v[190:193], v[38:41]
	v_mfma_f32_16x16x32_bf16 v[34:37], v[174:177], v[190:193], v[34:37]
	v_mfma_f32_16x16x32_bf16 v[22:25], v[166:169], v[208:211], v[22:25]
	v_mfma_f32_16x16x32_bf16 v[18:21], v[174:177], v[208:211], v[18:21]
	v_mfma_f32_16x16x32_bf16 v[6:9], v[166:169], v[216:219], v[6:9]
	v_mfma_f32_16x16x32_bf16 v[2:5], v[174:177], v[216:219], v[2:5]
	s_barrier
	s_setprio 0
	s_add_i32 s41, s41, 2
	s_add_u32 s39, s39, 0x100
	s_addc_u32 s40, s40, 0
	s_add_u32 s58, s58, 0x100
	s_addc_u32 s59, s59, 0
	s_cmp_gt_u32 s41, 13
	s_cbranch_scc0 .LBB0_647
	s_and_b64 vcc, exec, s[4:5]
	s_cbranch_vccz .LBB0_650
	s_barrier
